# K-loops of both SwiGLU-up phases and the first FFN-down phase: LDS tile relayout so every LDS-DMA instruction fetches 8 full 128-byte lines
# baseline (speedup 1.0000x reference)
; #define LAS __attribute__((address_space(3)))
; #define PG8_STAGEA(bufoff, gbase) PG8_STAGE_(bufoff, gbase, voffA)
; #define PG8_STAGEB(bufoff, gbase) PG8_STAGE_(bufoff, gbase, voffB)
; template <int EK, int SK = -1>
; __device__ __forceinline__ void gemm_phase(LAS unsigned char* lds, const bf16_t* A, const bf16_t* Bt, int nM, int N, int K, const EpiArgs& E) {
;     const int tid = threadIdx.x, wid = __builtin_amdgcn_readfirstlane(tid >> 6), lane = tid & 63, wr = wid >> 2, wc = wid & 3, fr = lane & 15, fq = lane >> 4;
;     const int nt = K / BK;
;     SOrder S; S.init(nM, N, (int)gridDim.x, (int)blockIdx.x);
;     LAS float* rtab = (LAS float*)(lds + RTAB_OFF);
;     unsigned voffA[2], voffB[2];
; #pragma unroll
;     for (int i = 0; i < 2; ++i) { int R, C; stage_rc(tid * 16 + i * 8192, R, C); const int Rb = (R & ~31) + perm32(R & 31);
;         voffA[i] = (unsigned)(R * K + C) * 2u; voffB[i] = (unsigned)(Rb * K + C) * 2u; }
;     const size_t kstep = (size_t)(BK * 2);
;     const size_t hstep = (size_t)HALF * K * 2;
;     const size_t tstep = 2 * hstep;
;     const unsigned ldsw = (unsigned)wid * 1024u;
;     const int aoff = lds_byte(wr * 64 + fr, fq * 8), boff = lds_byte(wc * 32 + fr, fq * 8);
;     ...
;     Unit cur, nxt; int ui = 0;
;     if (!S.next(0, cur)) { if (SK >= 0) skinny_phase<(SK >= 0 ? SK : 0)>(lds + 32768, (LAS float*)(lds + SRED_OFF), A, Bt, N, K, E); return; }
;     f32x4 acc[2][2][4][2];
; #pragma unroll
;     for (int a = 0; a < 2; ++a)
; #pragma unroll
;         for (int b = 0; b < 2; ++b)
; #pragma unroll
;             for (int m = 0; m < 4; ++m)
; #pragma unroll
;                 for (int n = 0; n < 2; ++n) acc[a][b][m][n] = (f32x4){0.f, 0.f, 0.f, 0.f};
;     bf16x8 At[4][2], B0[2][2], B1[2][2];
;     const char* cA = (const char*)A + (size_t)cur.pm * tstep; const char* cB = (const char*)Bt + (size_t)cur.pn * tstep;
;     PG8_STAGEB(PG8_SB(0, 0), cB); PG8_STAGEB(PG8_SB(0, 1), cB + hstep); PG8_STAGEA(PG8_SA(0, 0), cA); PG8_STAGEA(PG8_SA(0, 1), cA + hstep);
;     f32x4 tq[4][4]; bool okq[4];
;     if (EK != EK_RES && EK != EK_FINAL) {
; #pragma unroll
;         for (int j = 0; j < 4; ++j) { Unit uu; okq[j] = S.next((tid >> 8) + 2 * j, uu);
;             if (okq[j]) { const f32x4* sp = (const f32x4*)(E.stIn + (size_t)(uu.pm * BM + (tid & 255)) * 16); tq[j][0] = sp[0]; tq[j][1] = sp[1]; tq[j][2] = sp[2]; tq[j][3] = sp[3]; } }
.LBB0_494:
	s_load_dword s80, s[0:1], 0xb8
	v_lshrrev_b32_e32 v1, 2, v0
	v_lshrrev_b32_e32 v156, 5, v0
	s_andn2_b64 vcc, exec, s[4:5]
	v_lshlrev_b32_e32 v157, 2, v0
	s_cbranch_vccnz .LBB0_546
	s_waitcnt vmcnt(0)
	v_lshlrev_b32_e32 v4, 1, v1
	v_lshlrev_b32_e32 v2, 4, v0
	v_and_b32_e32 v3, 32, v0
	v_and_b32_e32 v4, 24, v4
	v_and_b32_e32 v5, 4, v156
	v_and_b32_e32 v6, 3, v1
	v_and_b32_e32 v76, 15, v1
	v_bitop3_b32 v74, v2, v3, 48 bitop3:0x6c
	v_and_b32_e32 v75, 64, v0
	v_or3_b32 v4, v5, v6, v4
	v_lshrrev_b32_e32 v5, 3, v0
	v_or_b32_e32 v77, 0x2000, v2
	s_add_u32 s81, s30, 0x600000
	v_or_b32_e32 v3, v74, v75
	v_and_or_b32 v6, v5, 48, v76
	v_and_or_b32 v5, v5, 32, v4
	v_lshrrev_b32_e32 v2, 7, v77
	s_waitcnt lgkmcnt(0)
	s_movk_i32 s3, 0x70
	s_addc_u32 s82, s31, 0
	v_and_or_b32 v5, v2, s3, v76
	s_movk_i32 s3, 0x60
	s_lshr_b32 s52, s53, 6
	s_ashr_i32 s17, s16, 31
	s_ashr_i32 s15, s14, 31
	v_and_or_b32 v2, v2, s3, v4
	s_lshl_b32 s83, s52, 10
	s_ashr_i32 s3, s2, 31
	s_lshl_b64 s[4:5], s[16:17], 19
	s_lshl_b64 s[6:7], s[14:15], 19
	s_add_u32 s74, s81, s6
	s_addc_u32 s75, s82, s7
	s_add_i32 s15, s83, 0
	s_add_i32 m0, s15, 0x10000
	v_lshrrev_b32_e32 v232, 3, v0
	v_xor_b32_e32 v233, v0, v232
	v_and_b32_e32 v233, 7, v233
	v_lshlrev_b32_e32 v233, 4, v233
	v_bfe_u32 v234, v0, 3, 2
	v_bfe_u32 v235, v0, 7, 1
	v_lshl_or_b32 v234, v235, 2, v234
	v_bfe_u32 v235, v0, 5, 1
	v_lshl_or_b32 v234, v235, 3, v234
	v_bfe_u32 v235, v0, 6, 1
	v_lshl_or_b32 v234, v235, 4, v234
	v_bfe_u32 v235, v0, 8, 1
	v_lshl_or_b32 v234, v235, 5, v234
	v_lshl_or_b32 v130, v232, 11, v233
	v_lshl_or_b32 v132, v234, 11, v233
	v_add_u32_e32 v134, 0x20000, v130
	v_add_u32_e32 v136, 0x20000, v132
	global_load_lds_dwordx4 v132, s[74:75]
	s_add_i32 m0, s15, 0x12000
	s_add_u32 s6, s74, 0x40000
	global_load_lds_dwordx4 v136, s[74:75]
	s_addc_u32 s7, s75, 0
	s_add_i32 m0, s15, 0x14000
	global_load_lds_dwordx4 v132, s[6:7]
	s_add_i32 m0, s15, 0x16000
	s_add_u32 s38, s62, s4
	s_addc_u32 s39, s63, s5
	s_add_i32 s17, s15, 0x2000
	global_load_lds_dwordx4 v136, s[6:7]
	s_mov_b32 m0, s15
	s_add_u32 s4, s38, 0x40000
	global_load_lds_dwordx4 v130, s[38:39]
	s_mov_b32 m0, s17
	s_addc_u32 s5, s39, 0
	s_add_i32 s84, s15, 0x4000
	global_load_lds_dwordx4 v134, s[38:39]
	s_mov_b32 m0, s84
	s_add_i32 s85, s15, 0x6000
	global_load_lds_dwordx4 v130, s[4:5]
	s_mov_b32 m0, s85
	v_lshrrev_b32_e32 v50, 8, v0
	global_load_lds_dwordx4 v134, s[4:5]
	v_mov_b64_e32 v[2:3], s[2:3]
	v_mad_i64_i32 v[2:3], s[4:5], s80, v50, v[2:3]
	v_mov_b32_e32 v133, 0
	s_mov_b64 s[4:5], 0x596
	v_mov_b32_e32 v137, v133
	v_mov_b32_e32 v131, v133
	v_mov_b32_e32 v135, v133
	v_and_b32_e32 v78, 0xff, v0
	v_cmp_gt_i64_e32 vcc, s[4:5], v[2:3]
	s_and_saveexec_b64 s[6:7], vcc
	s_cbranch_execz .LBB0_501
	v_ashrrev_i32_e32 v3, 31, v2
	v_lshrrev_b32_e32 v3, 29, v3
	v_add_u32_e32 v4, v2, v3
	v_and_b32_e32 v3, -8, v4
	v_sub_u32_e32 v3, v2, v3
	v_cmp_lt_i32_e64 s[4:5], 5, v3
	s_and_saveexec_b64 s[8:9], s[4:5]
	s_xor_b64 s[4:5], exec, s[8:9]
	s_movk_i32 s8, 0xb2
	v_mad_u64_u32 v[2:3], s[8:9], v3, s8, 6
	s_or_saveexec_b64 s[4:5], s[4:5]
	v_ashrrev_i32_e32 v4, 3, v4
	s_xor_b64 exec, exec, s[4:5]
	s_movk_i32 s8, 0xb3
	v_mul_lo_u32 v2, v3, s8
	s_or_b64 exec, exec, s[4:5]
	v_add_u32_e32 v2, v2, v4
	s_mov_b32 s4, 0x2e8ba2e9
	v_mul_hi_i32 v3, v2, s4
	v_lshrrev_b32_e32 v4, 31, v3
	v_ashrrev_i32_e32 v3, 4, v3
	v_add_u32_e32 v3, v3, v4
	v_lshlrev_b32_e32 v4, 2, v3
	v_sub_u32_e32 v5, 0x41, v4
	v_min_i32_e32 v5, 4, v5
	v_sub_u32_e32 v6, 0, v5
	v_max_i32_e32 v5, v5, v6
	v_cvt_f32_u32_e32 v6, v5
	s_movk_i32 s4, 0x58
	v_mul_lo_u32 v3, v3, s4
	v_sub_u32_e32 v2, v2, v3
	v_rcp_iflag_f32_e32 v6, v6
	v_sub_u32_e32 v7, 0, v2
	v_ashrrev_i32_e32 v3, 31, v2
	v_max_i32_e32 v2, v2, v7
	v_mul_f32_e32 v6, 0x4f7ffffe, v6
	v_cvt_u32_f32_e32 v6, v6
	v_sub_u32_e32 v7, 0, v5
	v_mul_lo_u32 v7, v7, v6
	v_mul_hi_u32 v7, v6, v7
	v_add_u32_e32 v6, v6, v7
	v_mul_hi_u32 v6, v2, v6
	v_mul_lo_u32 v6, v6, v5
	v_sub_u32_e32 v2, v2, v6
	v_sub_u32_e32 v6, v2, v5
	v_cmp_ge_u32_e64 s[4:5], v2, v5
	s_nop 1
	v_cndmask_b32_e64 v2, v2, v6, s[4:5]
	v_sub_u32_e32 v6, v2, v5
	v_cmp_ge_u32_e64 s[4:5], v2, v5
	s_nop 1
	v_cndmask_b32_e64 v2, v2, v6, s[4:5]
	v_xor_b32_e32 v2, v2, v3
	v_sub_u32_e32 v2, v2, v3
	v_add_u32_e32 v2, v4, v2
	v_lshl_or_b32 v2, v2, 8, v78
	v_ashrrev_i32_e32 v3, 31, v2
	v_lshlrev_b64 v[2:3], 6, v[2:3]
	v_lshl_add_u64 v[14:15], s[12:13], 0, v[2:3]
	global_load_dwordx4 v[2:5], v[14:15], off offset:48
	global_load_dwordx4 v[10:13], v[14:15], off offset:32
	global_load_dwordx4 v[6:9], v[14:15], off offset:16
	s_nop 0
	global_load_dwordx4 v[14:17], v[14:15], off

; #define LAS __attribute__((address_space(3)))
; __device__ __forceinline__ float hsum4(f32x4 v) { return (v[0] + v[1]) + (v[2] + v[3]); }
; #define PG8_STAGEA(bufoff, gbase) PG8_STAGE_(bufoff, gbase, voffA)
; #define PG8_STAGEB(bufoff, gbase) PG8_STAGE_(bufoff, gbase, voffB)
; template <int EK, int SK = -1>
; __device__ __forceinline__ void gemm_phase(LAS unsigned char* lds, const bf16_t* A, const bf16_t* Bt, int nM, int N, int K, const EpiArgs& E) {
;     ...
;     const int aoff = lds_byte(wr * 64 + fr, fq * 8), boff = lds_byte(wc * 32 + fr, fq * 8);
;     ...
;     Unit cur, nxt; int ui = 0;
;     if (!S.next(0, cur)) { if (SK >= 0) skinny_phase<(SK >= 0 ? SK : 0)>(lds + 32768, (LAS float*)(lds + SRED_OFF), A, Bt, N, K, E); return; }
;     f32x4 acc[2][2][4][2];
; #pragma unroll
;     for (int a = 0; a < 2; ++a)
; #pragma unroll
;         for (int b = 0; b < 2; ++b)
; #pragma unroll
;             for (int m = 0; m < 4; ++m)
; #pragma unroll
;                 for (int n = 0; n < 2; ++n) acc[a][b][m][n] = (f32x4){0.f, 0.f, 0.f, 0.f};
;     bf16x8 At[4][2], B0[2][2], B1[2][2];
;     const char* cA = (const char*)A + (size_t)cur.pm * tstep; const char* cB = (const char*)Bt + (size_t)cur.pn * tstep;
;     PG8_STAGEB(PG8_SB(0, 0), cB); PG8_STAGEB(PG8_SB(0, 1), cB + hstep); PG8_STAGEA(PG8_SA(0, 0), cA); PG8_STAGEA(PG8_SA(0, 1), cA + hstep);
;     f32x4 tq[4][4]; bool okq[4];
;     if (EK != EK_RES && EK != EK_FINAL) {
; #pragma unroll
;         for (int j = 0; j < 4; ++j) { Unit uu; okq[j] = S.next((tid >> 8) + 2 * j, uu);
;             if (okq[j]) { const f32x4* sp = (const f32x4*)(E.stIn + (size_t)(uu.pm * BM + (tid & 255)) * 16); tq[j][0] = sp[0]; tq[j][1] = sp[1]; tq[j][2] = sp[2]; tq[j][3] = sp[3]; } }
;     }
;     if (SK >= 0) skinny_phase<(SK >= 0 ? SK : 0)>(lds + 32768, (LAS float*)(lds + SRED_OFF), A, Bt, N, K, E);
;     if (EK != EK_RES && EK != EK_FINAL) {
; #pragma unroll
;         for (int j = 0; j < 4; ++j) if (okq[j]) { const float s_ = (hsum4(tq[j][0]) + hsum4(tq[j][1])) + (hsum4(tq[j][2]) + hsum4(tq[j][3]));
;             rtab[((tid >> 8) + 2 * j) * 256 + (tid & 255)] = rsqrtf(s_ * (1.0f / 1024.0f) + EPS); }
;         __syncthreads();
;     }
;     if (wr == 1) PG8_BAR;
;     PG8_WAIT_V(2); PG8_BAR;
;     PG8_STAGEB(PG8_SB(1, 0), cB + kstep); PG8_STAGEA(PG8_SA(1, 0), cA + kstep); PG8_STAGEB(PG8_SB(1, 1), cB + hstep + kstep);
;     PG8_WAIT_V(6); PG8_BAR;
.LBB0_529:
	v_lshrrev_b32_e32 v3, 1, v0
	v_and_b32_e32 v2, 15, v0
	v_and_b32_e32 v4, 24, v3
	v_lshlrev_b32_e32 v3, 1, v4
	v_lshlrev_b32_e32 v6, 2, v2
	v_lshl_or_b32 v158, s4, 6, v2
	v_lshl_or_b32 v5, v2, 6, v3
	s_lshl_b32 s5, s4, 13
	v_and_b32_e32 v2, 32, v6
	v_bitop3_b32 v5, v5, s5, v2 bitop3:0xde
	s_lshl_b32 s5, s52, 5
	s_and_b32 s5, s5, 0x60
	v_lshlrev_b32_e32 v2, 6, v0
	s_movk_i32 s6, 0x3c0
	v_and_or_b32 v2, v2, s6, v3
	s_lshl_b32 s6, s5, 7
	v_and_b32_e32 v3, 32, v157
	s_mov_b64 s[10:11], 0x80
	v_and_b32_e32 v232, 15, v0
	v_bfe_u32 v233, v0, 4, 2
	v_and_b32_e32 v234, 7, v232
	v_xor_b32_e32 v233, v233, v234
	v_lshlrev_b32_e32 v233, 4, v233
	v_lshl_or_b32 v233, v234, 7, v233
	v_lshrrev_b32_e32 v232, 3, v232
	v_bfe_u32 v234, v0, 6, 2
	v_lshl_or_b32 v234, v234, 2, v232
	v_lshl_or_b32 v159, v234, 10, v233
	v_xor_b32_e32 v239, 64, v159
	s_add_i32 m0, s15, 0x18000
	v_lshl_add_u64 v[2:3], v[72:73], 0, s[10:11]
	s_waitcnt vmcnt(2)
	s_barrier
	global_load_lds_dwordx4 v[2:3], off
	v_lshl_add_u64 v[2:3], v[70:71], 0, s[10:11]
	s_add_i32 m0, s15, 0x1a000
	s_add_i32 s86, s15, 0x8000
	s_add_i32 s87, s15, 0xa000
	global_load_lds_dwordx4 v[2:3], off
	v_lshl_add_u64 v[2:3], v[68:69], 0, s[10:11]
	s_mov_b32 m0, s86
	s_add_u32 s12, s74, 0x40080
	global_load_lds_dwordx4 v[2:3], off
	v_lshl_add_u64 v[2:3], v[66:67], 0, s[10:11]
	s_mov_b32 m0, s87
	s_addc_u32 s13, s75, 0
	global_load_lds_dwordx4 v[2:3], off
	s_add_i32 m0, s15, 0x1c000
	v_lshl_add_u64 v[2:3], s[12:13], 0, v[132:133]
	global_load_lds_dwordx4 v[2:3], off
	v_lshl_add_u64 v[2:3], s[12:13], 0, v[136:137]
	s_add_i32 m0, s15, 0x1e000
	v_or_b32_e32 v161, s5, v4
	global_load_lds_dwordx4 v[2:3], off
	v_lshlrev_b32_e32 v2, 8, v0
	v_and_b32_e32 v2, 0x18000, v2
	v_lshlrev_b32_e32 v4, 11, v76
	v_or3_b32 v2, v74, v2, v4
	s_mov_b64 s[6:7], 0x40080
	v_add_u32_e32 v2, v2, v75
	v_mov_b32_e32 v3, 0
	s_lshl_b32 s4, s4, 8
	v_lshl_add_u64 v[138:139], v[130:131], 0, s[6:7]
	v_lshlrev_b32_e32 v2, 4, v77
	s_add_i32 s4, s4, 0
	v_and_b32_e32 v2, 0x38000, v2
	s_waitcnt vmcnt(6)
	s_add_i32 s4, s4, 0x20010
	v_or3_b32 v2, v74, v2, v4
	s_cmpk_lt_u32 s53, 0x100
	v_add_u32_e32 v2, v2, v75
	s_mov_b32 s52, 0
	v_add_u32_e32 v160, s4, v6
	s_cselect_b64 s[12:13], -1, 0
	v_lshl_add_u64 v[140:141], v[134:135], 0, s[6:7]
	v_mov_b64_e32 v[142:143], 0x596
	v_mov_b64_e32 v[144:145], 0x595
	s_add_i32 s88, 0, 0x10000
	s_add_i32 s89, 0, 0x14000
	v_and_b32_e32 v232, 15, v0
	v_bfe_u32 v233, v0, 4, 2
	v_and_b32_e32 v234, 7, v232
	v_xor_b32_e32 v233, v233, v234
	v_lshlrev_b32_e32 v233, 4, v233
	v_lshl_or_b32 v233, v234, 7, v233
	v_lshrrev_b32_e32 v232, 3, v232
	v_lshrrev_b32_e32 v234, 8, v0
	v_lshl_or_b32 v234, v234, 3, v232
	v_lshl_or_b32 v162, v234, 10, v233
	v_xor_b32_e32 v238, 64, v162
	s_movk_i32 s90, 0x1600
	v_mov_b32_e32 v2, v3
	s_barrier
	s_branch .LBB0_531

; #define PG8_STAGEA(bufoff, gbase) PG8_STAGE_(bufoff, gbase, voffA)
; #define PG8_STAGEB(bufoff, gbase) PG8_STAGE_(bufoff, gbase, voffB)
; #define PG8_LDA(dst, b, h) do { _Pragma("unroll") for (int m = 0; m < 4; ++m) _Pragma("unroll") for (int k = 0; k < 2; ++k) dst[m][k] = *(const LAS bf16x8*)(lds + PG8_SA(b, h) + aoff + m * 2048 + k * 1024); } while (0)
; #define PG8_LDB(dst, b, h) do { _Pragma("unroll") for (int n = 0; n < 2; ++n) _Pragma("unroll") for (int k = 0; k < 2; ++k) dst[n][k] = *(const LAS bf16x8*)(lds + PG8_SB(b, h) + boff + n * 2048 + k * 1024); } while (0)
; #define PG8_MMA(ai, bj, At, Bt_) do { __builtin_amdgcn_s_setprio(1); _Pragma("unroll") for (int m = 0; m < 4; ++m) _Pragma("unroll") for (int n = 0; n < 2; ++n) _Pragma("unroll") for (int k = 0; k < 2; ++k) \
;         acc[ai][bj][m][n] = __builtin_amdgcn_mfma_f32_16x16x32_bf16(Bt_[n][k], At[m][k], acc[ai][bj][m][n], 0, 0, 0); __builtin_amdgcn_s_setprio(0); } while (0)
; #define PG8_WAIT_V(n) asm volatile("s_waitcnt vmcnt(" #n ")" ::: "memory")
; #define PG8_WAIT_L(n) asm volatile("s_waitcnt lgkmcnt(" #n ")" ::: "memory")
; #define PG8_BAR __builtin_amdgcn_s_barrier()
; template <int EK, int SK = -1>
; __device__ __forceinline__ void gemm_phase(LAS unsigned char* lds, const bf16_t* A, const bf16_t* Bt, int nM, int N, int K, const EpiArgs& E) {
;     ...
;         const bool has_next = S.next(ui + 1, nxt);
;         const char* nA = has_next ? (const char*)A + (size_t)nxt.pm * tstep : cA; const char* nB = has_next ? (const char*)Bt + (size_t)nxt.pn * tstep : cB;
;         for (int t = 0; t < nt; t += 2) {
;             const bool last = (t == nt - 2);
;             const char* a1 = cA + (size_t)(t + 1) * kstep;
;             const char* a2 = last ? nA : cA + (size_t)(t + 2) * kstep; const char* b2 = last ? nB : cB + (size_t)(t + 2) * kstep;
;             const char* a3 = a2 + kstep; const char* b3 = b2 + kstep;
;             PG8_LDB(B0, 0, 0); PG8_LDB(B1, 0, 1); PG8_SCHED; PG8_LDA(At, 0, 0); PG8_STAGEA(PG8_SA(1, 1), a1 + hstep);
;             PG8_WAIT_V(8); PG8_WAIT_L(0); PG8_BAR; PG8_MMA(0, 0, At, B0); PG8_MMA(0, 1, At, B1); PG8_BAR; PG8_SCHED;
;             PG8_LDA(At, 0, 1); PG8_STAGEB(PG8_SB(0, 0), b2); PG8_STAGEB(PG8_SB(0, 1), b2 + hstep); PG8_STAGEA(PG8_SA(0, 0), a2);
;             PG8_WAIT_V(8); PG8_WAIT_L(0); PG8_BAR; PG8_MMA(1, 0, At, B0); PG8_MMA(1, 1, At, B1); PG8_BAR; PG8_SCHED;
.LBB0_537:
	s_add_u32 s54, s74, 0x100
	s_addc_u32 s55, s75, 0
	s_ashr_i32 s69, s68, 31
	s_lshl_b64 s[56:57], s[68:69], 19
	s_add_u32 s72, s62, s56
	s_addc_u32 s73, s63, s57
	s_and_b64 s[56:57], s[6:7], exec
	s_cselect_b32 s56, s73, s39
	s_cselect_b32 s57, s72, s38
	s_ashr_i32 s41, s40, 31
	s_lshl_b64 s[58:59], s[40:41], 19
	s_add_u32 s70, s81, s58
	s_addc_u32 s71, s82, s59
	s_and_b64 s[58:59], s[6:7], exec
	s_cselect_b32 s41, s71, s75
	s_cselect_b32 s58, s70, s74
	v_lshl_add_u64 v[146:147], s[38:39], 0, v[138:139]
	v_lshl_add_u64 v[148:149], s[38:39], 0, v[140:141]
	s_mov_b32 s59, -2
	s_mov_b64 s[74:75], 0
	v_add_u32_e32 v154, s88, v159
	v_add_u32_e32 v237, s88, v239
	ds_read_b128 v[150:153], v154
	ds_read_b128 v[164:167], v237
	ds_read_b128 v[168:171], v154 offset:2048
	ds_read_b128 v[172:175], v237 offset:2048
	v_add_u32_e32 v154, s89, v159
	v_add_u32_e32 v237, s89, v239
	s_add_u32 s69, s38, s74
	ds_read_b128 v[176:179], v154
	ds_read_b128 v[180:183], v237
	ds_read_b128 v[184:187], v154 offset:2048
	ds_read_b128 v[188:191], v237 offset:2048
	s_addc_u32 s76, s39, s75
	s_add_u32 s69, s69, 0x100
	s_addc_u32 s76, s76, 0
	s_add_u32 s91, s54, s74
	s_addc_u32 s77, s55, s75
	s_cmpk_eq_i32 s74, 0x700
	s_cselect_b32 s79, s56, s76
	s_cselect_b32 s78, s57, s69
	s_cselect_b32 s77, s41, s77
	s_cselect_b32 s76, s58, s91
	v_lshl_add_u64 v[154:155], v[146:147], 0, s[74:75]
	s_add_i32 m0, s15, 0xc000
	ds_read_b128 v[192:195], v162
	ds_read_b128 v[196:199], v238
	ds_read_b128 v[200:203], v162 offset:2048
	ds_read_b128 v[204:207], v238 offset:2048
	ds_read_b128 v[208:211], v162 offset:4096
	ds_read_b128 v[212:215], v238 offset:4096
	ds_read_b128 v[216:219], v162 offset:6144
	ds_read_b128 v[220:223], v238 offset:6144
	global_load_lds_dwordx4 v[154:155], off
	v_lshl_add_u64 v[154:155], v[148:149], 0, s[74:75]
	s_add_i32 m0, s15, 0xe000
	s_nop 0
	global_load_lds_dwordx4 v[154:155], off
	s_waitcnt vmcnt(8)
	s_waitcnt lgkmcnt(0)
	s_barrier
	s_waitcnt lgkmcnt(0)
	v_mfma_f32_16x16x32_bf16 v[110:113], v[150:153], v[192:195], 0
	v_mfma_f32_16x16x32_bf16 v[106:109], v[168:171], v[192:195], 0
	v_mfma_f32_16x16x32_bf16 v[102:105], v[150:153], v[200:203], 0
	v_mfma_f32_16x16x32_bf16 v[98:101], v[168:171], v[200:203], 0
	v_mfma_f32_16x16x32_bf16 v[94:97], v[150:153], v[208:211], 0
	v_mfma_f32_16x16x32_bf16 v[90:93], v[168:171], v[208:211], 0
	v_mfma_f32_16x16x32_bf16 v[86:89], v[150:153], v[216:219], 0
	v_mfma_f32_16x16x32_bf16 v[82:85], v[168:171], v[216:219], 0
	v_mfma_f32_16x16x32_bf16 v[110:113], v[164:167], v[196:199], v[110:113]
	v_mfma_f32_16x16x32_bf16 v[106:109], v[172:175], v[196:199], v[106:109]
	v_mfma_f32_16x16x32_bf16 v[102:105], v[164:167], v[204:207], v[102:105]
	v_mfma_f32_16x16x32_bf16 v[98:101], v[172:175], v[204:207], v[98:101]
	v_mfma_f32_16x16x32_bf16 v[94:97], v[164:167], v[212:215], v[94:97]
	v_mfma_f32_16x16x32_bf16 v[90:93], v[172:175], v[212:215], v[90:93]
	v_mfma_f32_16x16x32_bf16 v[86:89], v[164:167], v[220:223], v[86:89]
	v_mfma_f32_16x16x32_bf16 v[82:85], v[172:175], v[220:223], v[82:85]
	v_mfma_f32_16x16x32_bf16 v[78:81], v[176:179], v[192:195], 0
	v_mfma_f32_16x16x32_bf16 v[74:77], v[184:187], v[192:195], 0
	v_mfma_f32_16x16x32_bf16 v[70:73], v[176:179], v[200:203], 0
	v_mfma_f32_16x16x32_bf16 v[66:69], v[184:187], v[200:203], 0
	v_mfma_f32_16x16x32_bf16 v[62:65], v[176:179], v[208:211], 0
	v_mfma_f32_16x16x32_bf16 v[58:61], v[184:187], v[208:211], 0
	v_mfma_f32_16x16x32_bf16 v[54:57], v[176:179], v[216:219], 0
	v_mfma_f32_16x16x32_bf16 v[50:53], v[184:187], v[216:219], 0
	v_mfma_f32_16x16x32_bf16 v[78:81], v[180:183], v[196:199], v[78:81]
	v_mfma_f32_16x16x32_bf16 v[74:77], v[188:191], v[196:199], v[74:77]
	v_mfma_f32_16x16x32_bf16 v[70:73], v[180:183], v[204:207], v[70:73]
	v_mfma_f32_16x16x32_bf16 v[66:69], v[188:191], v[204:207], v[66:69]
	v_mfma_f32_16x16x32_bf16 v[62:65], v[180:183], v[212:215], v[62:65]
	v_mfma_f32_16x16x32_bf16 v[58:61], v[188:191], v[212:215], v[58:61]
	v_mfma_f32_16x16x32_bf16 v[54:57], v[180:183], v[220:223], v[54:57]
	v_mfma_f32_16x16x32_bf16 v[50:53], v[188:191], v[220:223], v[50:53]
	s_barrier
	s_add_i32 s69, s88, s83
	v_lshl_add_u64 v[154:155], s[76:77], 0, v[132:133]
	s_mov_b32 m0, s69
	ds_read_b128 v[192:195], v162 offset:16384
	ds_read_b128 v[196:199], v238 offset:16384
	ds_read_b128 v[200:203], v162 offset:18432
	ds_read_b128 v[204:207], v238 offset:18432
	ds_read_b128 v[208:211], v162 offset:20480
	ds_read_b128 v[212:215], v238 offset:20480
	ds_read_b128 v[216:219], v162 offset:22528
	ds_read_b128 v[220:223], v238 offset:22528
	global_load_lds_dwordx4 v[154:155], off
	s_add_i32 m0, s69, 0x2000
	s_add_u32 s92, s76, 0x40000
	v_lshl_add_u64 v[224:225], s[76:77], 0, v[136:137]
	s_addc_u32 s93, s77, 0
	s_add_i32 s69, s89, s83
	global_load_lds_dwordx4 v[224:225], off
	v_lshl_add_u64 v[226:227], s[92:93], 0, v[132:133]
	s_mov_b32 m0, s69
	v_lshl_add_u64 v[228:229], s[78:79], 0, v[134:135]
	global_load_lds_dwordx4 v[226:227], off
	v_lshl_add_u64 v[226:227], s[92:93], 0, v[136:137]
	s_add_i32 m0, s69, 0x2000
	s_nop 0
	global_load_lds_dwordx4 v[226:227], off
	v_lshl_add_u64 v[226:227], s[78:79], 0, v[130:131]
	s_mov_b32 m0, s15
	s_nop 0
	global_load_lds_dwordx4 v[226:227], off
	s_mov_b32 m0, s17
	s_nop 0
	global_load_lds_dwordx4 v[228:229], off
	s_waitcnt vmcnt(8)
	s_waitcnt lgkmcnt(0)
	s_barrier
; #define PG8_STAGEA(bufoff, gbase) PG8_STAGE_(bufoff, gbase, voffA)
; #define PG8_STAGEB(bufoff, gbase) PG8_STAGE_(bufoff, gbase, voffB)
; #define PG8_LDA(dst, b, h) do { _Pragma("unroll") for (int m = 0; m < 4; ++m) _Pragma("unroll") for (int k = 0; k < 2; ++k) dst[m][k] = *(const LAS bf16x8*)(lds + PG8_SA(b, h) + aoff + m * 2048 + k * 1024); } while (0)
; #define PG8_LDB(dst, b, h) do { _Pragma("unroll") for (int n = 0; n < 2; ++n) _Pragma("unroll") for (int k = 0; k < 2; ++k) dst[n][k] = *(const LAS bf16x8*)(lds + PG8_SB(b, h) + boff + n * 2048 + k * 1024); } while (0)
; #define PG8_MMA(ai, bj, At, Bt_) do { __builtin_amdgcn_s_setprio(1); _Pragma("unroll") for (int m = 0; m < 4; ++m) _Pragma("unroll") for (int n = 0; n < 2; ++n) _Pragma("unroll") for (int k = 0; k < 2; ++k) \
;         acc[ai][bj][m][n] = __builtin_amdgcn_mfma_f32_16x16x32_bf16(Bt_[n][k], At[m][k], acc[ai][bj][m][n], 0, 0, 0); __builtin_amdgcn_s_setprio(0); } while (0)
; #define PG8_WAIT_V(n) asm volatile("s_waitcnt vmcnt(" #n ")" ::: "memory")
; #define PG8_WAIT_L(n) asm volatile("s_waitcnt lgkmcnt(" #n ")" ::: "memory")
; #define PG8_BAR __builtin_amdgcn_s_barrier()
; #define PG8_SCHED __builtin_amdgcn_sched_barrier(0)
; template <int EK, int SK = -1>
; __device__ __forceinline__ void gemm_phase(LAS unsigned char* lds, const bf16_t* A, const bf16_t* Bt, int nM, int N, int K, const EpiArgs& E) {
;     ...
;             PG8_WAIT_V(8); PG8_WAIT_L(0); PG8_BAR; PG8_MMA(1, 0, At, B0); PG8_MMA(1, 1, At, B1); PG8_BAR; PG8_SCHED;
;             PG8_LDB(B0, 1, 0); PG8_LDB(B1, 1, 1); PG8_SCHED; PG8_LDA(At, 1, 0); PG8_STAGEA(PG8_SA(0, 1), a2 + hstep);
;             PG8_WAIT_V(8); PG8_WAIT_L(0); PG8_BAR; PG8_MMA(0, 0, At, B0); PG8_MMA(0, 1, At, B1); PG8_BAR; PG8_SCHED;
;             PG8_LDA(At, 1, 1); PG8_STAGEB(PG8_SB(1, 0), b3); PG8_STAGEB(PG8_SB(1, 1), b3 + hstep); PG8_STAGEA(PG8_SA(1, 0), a3);
;             PG8_WAIT_V(8); PG8_WAIT_L(0); PG8_BAR; PG8_MMA(1, 0, At, B0); PG8_MMA(1, 1, At, B1); PG8_BAR; PG8_SCHED;
	s_waitcnt lgkmcnt(0)
	v_mfma_f32_16x16x32_bf16 v[46:49], v[150:153], v[192:195], 0
	v_mfma_f32_16x16x32_bf16 v[42:45], v[168:171], v[192:195], 0
	v_mfma_f32_16x16x32_bf16 v[38:41], v[150:153], v[200:203], 0
	v_mfma_f32_16x16x32_bf16 v[34:37], v[168:171], v[200:203], 0
	v_mfma_f32_16x16x32_bf16 v[30:33], v[150:153], v[208:211], 0
	v_mfma_f32_16x16x32_bf16 v[26:29], v[168:171], v[208:211], 0
	v_mfma_f32_16x16x32_bf16 v[22:25], v[150:153], v[216:219], 0
	v_mfma_f32_16x16x32_bf16 v[18:21], v[168:171], v[216:219], 0
	v_mfma_f32_16x16x32_bf16 v[46:49], v[164:167], v[196:199], v[46:49]
	v_mfma_f32_16x16x32_bf16 v[42:45], v[172:175], v[196:199], v[42:45]
	v_mfma_f32_16x16x32_bf16 v[38:41], v[164:167], v[204:207], v[38:41]
	v_mfma_f32_16x16x32_bf16 v[34:37], v[172:175], v[204:207], v[34:37]
	v_mfma_f32_16x16x32_bf16 v[30:33], v[164:167], v[212:215], v[30:33]
	v_mfma_f32_16x16x32_bf16 v[26:29], v[172:175], v[212:215], v[26:29]
	v_mfma_f32_16x16x32_bf16 v[22:25], v[164:167], v[220:223], v[22:25]
	v_mfma_f32_16x16x32_bf16 v[18:21], v[172:175], v[220:223], v[18:21]
	v_mfma_f32_16x16x32_bf16 v[14:17], v[176:179], v[192:195], 0
	v_mfma_f32_16x16x32_bf16 v[10:13], v[184:187], v[192:195], 0
	v_mfma_f32_16x16x32_bf16 v[6:9], v[176:179], v[200:203], 0
	v_mfma_f32_16x16x32_bf16 v[2:5], v[184:187], v[200:203], 0
	v_mfma_f32_16x16x32_bf16 v[114:117], v[176:179], v[208:211], 0
	v_mfma_f32_16x16x32_bf16 v[118:121], v[184:187], v[208:211], 0
	v_mfma_f32_16x16x32_bf16 v[122:125], v[176:179], v[216:219], 0
	v_mfma_f32_16x16x32_bf16 v[126:129], v[184:187], v[216:219], 0
	v_mfma_f32_16x16x32_bf16 v[14:17], v[180:183], v[196:199], v[14:17]
	v_mfma_f32_16x16x32_bf16 v[10:13], v[188:191], v[196:199], v[10:13]
	v_mfma_f32_16x16x32_bf16 v[6:9], v[180:183], v[204:207], v[6:9]
	v_mfma_f32_16x16x32_bf16 v[2:5], v[188:191], v[204:207], v[2:5]
	v_mfma_f32_16x16x32_bf16 v[114:117], v[180:183], v[212:215], v[114:117]
	v_mfma_f32_16x16x32_bf16 v[118:121], v[188:191], v[212:215], v[118:121]
	v_mfma_f32_16x16x32_bf16 v[122:125], v[180:183], v[220:223], v[122:125]
	v_mfma_f32_16x16x32_bf16 v[126:129], v[188:191], v[220:223], v[126:129]
	s_barrier
	s_add_i32 s69, 0, 0x18000
	v_add_u32_e32 v163, s69, v159
	v_add_u32_e32 v236, s69, v239
	s_add_i32 s91, 0, 0x1c000
	ds_read_b128 v[150:153], v163
	ds_read_b128 v[164:167], v236
	ds_read_b128 v[168:171], v163 offset:2048
	ds_read_b128 v[172:175], v236 offset:2048
	v_add_u32_e32 v163, s91, v159
	v_add_u32_e32 v236, s91, v239
	ds_read_b128 v[176:179], v163
	ds_read_b128 v[180:183], v236
	ds_read_b128 v[184:187], v163 offset:2048
	ds_read_b128 v[188:191], v236 offset:2048
	s_add_u32 s78, s78, 0x40000
	s_addc_u32 s79, s79, 0
	s_mov_b32 m0, s84
	v_lshl_add_u64 v[230:231], s[78:79], 0, v[130:131]
	ds_read_b128 v[192:195], v162 offset:32768
	ds_read_b128 v[196:199], v238 offset:32768
	ds_read_b128 v[200:203], v162 offset:34816
	ds_read_b128 v[204:207], v238 offset:34816
	ds_read_b128 v[208:211], v162 offset:36864
	ds_read_b128 v[212:215], v238 offset:36864
	ds_read_b128 v[216:219], v162 offset:38912
	ds_read_b128 v[220:223], v238 offset:38912
	global_load_lds_dwordx4 v[230:231], off
	v_lshl_add_u64 v[230:231], s[78:79], 0, v[134:135]
	s_mov_b32 m0, s85
	s_nop 0
	global_load_lds_dwordx4 v[230:231], off
	s_waitcnt vmcnt(8)
	s_waitcnt lgkmcnt(0)
	s_barrier
	s_waitcnt lgkmcnt(0)
	v_mfma_f32_16x16x32_bf16 v[110:113], v[150:153], v[192:195], v[110:113]
	v_mfma_f32_16x16x32_bf16 v[106:109], v[168:171], v[192:195], v[106:109]
	v_mfma_f32_16x16x32_bf16 v[102:105], v[150:153], v[200:203], v[102:105]
	v_mfma_f32_16x16x32_bf16 v[98:101], v[168:171], v[200:203], v[98:101]
	v_mfma_f32_16x16x32_bf16 v[94:97], v[150:153], v[208:211], v[94:97]
	v_mfma_f32_16x16x32_bf16 v[90:93], v[168:171], v[208:211], v[90:93]
	v_mfma_f32_16x16x32_bf16 v[86:89], v[150:153], v[216:219], v[86:89]
	v_mfma_f32_16x16x32_bf16 v[82:85], v[168:171], v[216:219], v[82:85]
	v_mfma_f32_16x16x32_bf16 v[110:113], v[164:167], v[196:199], v[110:113]
	v_mfma_f32_16x16x32_bf16 v[106:109], v[172:175], v[196:199], v[106:109]
	v_mfma_f32_16x16x32_bf16 v[102:105], v[164:167], v[204:207], v[102:105]
	v_mfma_f32_16x16x32_bf16 v[98:101], v[172:175], v[204:207], v[98:101]
	v_mfma_f32_16x16x32_bf16 v[94:97], v[164:167], v[212:215], v[94:97]
	v_mfma_f32_16x16x32_bf16 v[90:93], v[172:175], v[212:215], v[90:93]
	v_mfma_f32_16x16x32_bf16 v[86:89], v[164:167], v[220:223], v[86:89]
	v_mfma_f32_16x16x32_bf16 v[82:85], v[172:175], v[220:223], v[82:85]
	v_mfma_f32_16x16x32_bf16 v[78:81], v[176:179], v[192:195], v[78:81]
	v_mfma_f32_16x16x32_bf16 v[74:77], v[184:187], v[192:195], v[74:77]
	v_mfma_f32_16x16x32_bf16 v[70:73], v[176:179], v[200:203], v[70:73]
	v_mfma_f32_16x16x32_bf16 v[66:69], v[184:187], v[200:203], v[66:69]
	v_mfma_f32_16x16x32_bf16 v[62:65], v[176:179], v[208:211], v[62:65]
	v_mfma_f32_16x16x32_bf16 v[58:61], v[184:187], v[208:211], v[58:61]
	v_mfma_f32_16x16x32_bf16 v[54:57], v[176:179], v[216:219], v[54:57]
	v_mfma_f32_16x16x32_bf16 v[50:53], v[184:187], v[216:219], v[50:53]
	v_mfma_f32_16x16x32_bf16 v[78:81], v[180:183], v[196:199], v[78:81]
	v_mfma_f32_16x16x32_bf16 v[74:77], v[188:191], v[196:199], v[74:77]
	v_mfma_f32_16x16x32_bf16 v[70:73], v[180:183], v[204:207], v[70:73]
	v_mfma_f32_16x16x32_bf16 v[66:69], v[188:191], v[204:207], v[66:69]
	v_mfma_f32_16x16x32_bf16 v[62:65], v[180:183], v[212:215], v[62:65]
	v_mfma_f32_16x16x32_bf16 v[58:61], v[188:191], v[212:215], v[58:61]
	v_mfma_f32_16x16x32_bf16 v[54:57], v[180:183], v[220:223], v[54:57]
	v_mfma_f32_16x16x32_bf16 v[50:53], v[188:191], v[220:223], v[50:53]
	s_barrier
; #define PG8_STAGEA(bufoff, gbase) PG8_STAGE_(bufoff, gbase, voffA)
; #define PG8_STAGEB(bufoff, gbase) PG8_STAGE_(bufoff, gbase, voffB)
; #define PG8_LDA(dst, b, h) do { _Pragma("unroll") for (int m = 0; m < 4; ++m) _Pragma("unroll") for (int k = 0; k < 2; ++k) dst[m][k] = *(const LAS bf16x8*)(lds + PG8_SA(b, h) + aoff + m * 2048 + k * 1024); } while (0)
; #define PG8_LDB(dst, b, h) do { _Pragma("unroll") for (int n = 0; n < 2; ++n) _Pragma("unroll") for (int k = 0; k < 2; ++k) dst[n][k] = *(const LAS bf16x8*)(lds + PG8_SB(b, h) + boff + n * 2048 + k * 1024); } while (0)
; #define PG8_WAIT_V(n) asm volatile("s_waitcnt vmcnt(" #n ")" ::: "memory")
; #define PG8_WAIT_L(n) asm volatile("s_waitcnt lgkmcnt(" #n ")" ::: "memory")
; #define PG8_BAR __builtin_amdgcn_s_barrier()
; #define PG8_SCHED __builtin_amdgcn_sched_barrier(0)
; template <int EK, int SK = -1>
; __device__ __forceinline__ void gemm_phase(LAS unsigned char* lds, const bf16_t* A, const bf16_t* Bt, int nM, int N, int K, const EpiArgs& E) {
;     ...
;         for (int t = 0; t < nt; t += 2) {
;             const bool last = (t == nt - 2);
;             const char* a1 = cA + (size_t)(t + 1) * kstep;
;             const char* a2 = last ? nA : cA + (size_t)(t + 2) * kstep; const char* b2 = last ? nB : cB + (size_t)(t + 2) * kstep;
;             const char* a3 = a2 + kstep; const char* b3 = b2 + kstep;
;             PG8_LDB(B0, 0, 0); PG8_LDB(B1, 0, 1); PG8_SCHED; PG8_LDA(At, 0, 0); PG8_STAGEA(PG8_SA(1, 1), a1 + hstep);
;             PG8_WAIT_V(8); PG8_WAIT_L(0); PG8_BAR; PG8_MMA(0, 0, At, B0); PG8_MMA(0, 1, At, B1); PG8_BAR; PG8_SCHED;
;             PG8_LDA(At, 0, 1); PG8_STAGEB(PG8_SB(0, 0), b2); PG8_STAGEB(PG8_SB(0, 1), b2 + hstep); PG8_STAGEA(PG8_SA(0, 0), a2);
;             PG8_WAIT_V(8); PG8_WAIT_L(0); PG8_BAR; PG8_MMA(1, 0, At, B0); PG8_MMA(1, 1, At, B1); PG8_BAR; PG8_SCHED;
;             PG8_LDB(B0, 1, 0); PG8_LDB(B1, 1, 1); PG8_SCHED; PG8_LDA(At, 1, 0); PG8_STAGEA(PG8_SA(0, 1), a2 + hstep);
;             PG8_WAIT_V(8); PG8_WAIT_L(0); PG8_BAR; PG8_MMA(0, 0, At, B0); PG8_MMA(0, 1, At, B1); PG8_BAR; PG8_SCHED;
;             PG8_LDA(At, 1, 1); PG8_STAGEB(PG8_SB(1, 0), b3); PG8_STAGEB(PG8_SB(1, 1), b3 + hstep); PG8_STAGEA(PG8_SA(1, 0), a3);
;             PG8_WAIT_V(8); PG8_WAIT_L(0); PG8_BAR; PG8_MMA(1, 0, At, B0); PG8_MMA(1, 1, At, B1); PG8_BAR; PG8_SCHED;
	s_add_i32 s69, s69, s83
	v_lshl_add_u64 v[154:155], v[154:155], 0, s[10:11]
	s_mov_b32 m0, s69
	ds_read_b128 v[192:195], v162 offset:49152
	ds_read_b128 v[196:199], v238 offset:49152
	ds_read_b128 v[200:203], v162 offset:51200
	ds_read_b128 v[204:207], v238 offset:51200
	ds_read_b128 v[208:211], v162 offset:53248
	ds_read_b128 v[212:215], v238 offset:53248
	ds_read_b128 v[216:219], v162 offset:55296
	ds_read_b128 v[220:223], v238 offset:55296
	global_load_lds_dwordx4 v[154:155], off
	s_add_i32 m0, s69, 0x2000
	s_add_u32 s76, s76, 0x40080
	v_lshl_add_u64 v[154:155], v[224:225], 0, s[10:11]
	s_addc_u32 s77, s77, 0
	s_add_i32 s69, s91, s83
	global_load_lds_dwordx4 v[154:155], off
	v_lshl_add_u64 v[154:155], s[76:77], 0, v[132:133]
	s_mov_b32 m0, s69
	s_nop 0
	global_load_lds_dwordx4 v[154:155], off
	v_lshl_add_u64 v[154:155], s[76:77], 0, v[136:137]
	s_add_i32 m0, s69, 0x2000
	s_nop 0
	global_load_lds_dwordx4 v[154:155], off
	v_lshl_add_u64 v[154:155], v[226:227], 0, s[10:11]
	s_mov_b32 m0, s86
	s_nop 0
	global_load_lds_dwordx4 v[154:155], off
	v_lshl_add_u64 v[154:155], v[228:229], 0, s[10:11]
	s_mov_b32 m0, s87
	s_nop 0
	global_load_lds_dwordx4 v[154:155], off
	s_waitcnt vmcnt(8)
	s_waitcnt lgkmcnt(0)
	s_barrier
	s_waitcnt lgkmcnt(0)
	v_mfma_f32_16x16x32_bf16 v[46:49], v[150:153], v[192:195], v[46:49]
	v_mfma_f32_16x16x32_bf16 v[42:45], v[168:171], v[192:195], v[42:45]
	v_mfma_f32_16x16x32_bf16 v[38:41], v[150:153], v[200:203], v[38:41]
	v_mfma_f32_16x16x32_bf16 v[34:37], v[168:171], v[200:203], v[34:37]
	v_mfma_f32_16x16x32_bf16 v[30:33], v[150:153], v[208:211], v[30:33]
	v_mfma_f32_16x16x32_bf16 v[26:29], v[168:171], v[208:211], v[26:29]
	v_mfma_f32_16x16x32_bf16 v[22:25], v[150:153], v[216:219], v[22:25]
	v_mfma_f32_16x16x32_bf16 v[18:21], v[168:171], v[216:219], v[18:21]
	v_mfma_f32_16x16x32_bf16 v[46:49], v[164:167], v[196:199], v[46:49]
	v_mfma_f32_16x16x32_bf16 v[42:45], v[172:175], v[196:199], v[42:45]
	v_mfma_f32_16x16x32_bf16 v[38:41], v[164:167], v[204:207], v[38:41]
	v_mfma_f32_16x16x32_bf16 v[34:37], v[172:175], v[204:207], v[34:37]
	v_mfma_f32_16x16x32_bf16 v[30:33], v[164:167], v[212:215], v[30:33]
	v_mfma_f32_16x16x32_bf16 v[26:29], v[172:175], v[212:215], v[26:29]
	v_mfma_f32_16x16x32_bf16 v[22:25], v[164:167], v[220:223], v[22:25]
	v_mfma_f32_16x16x32_bf16 v[18:21], v[172:175], v[220:223], v[18:21]
	v_mfma_f32_16x16x32_bf16 v[14:17], v[176:179], v[192:195], v[14:17]
	v_mfma_f32_16x16x32_bf16 v[10:13], v[184:187], v[192:195], v[10:13]
	v_mfma_f32_16x16x32_bf16 v[6:9], v[176:179], v[200:203], v[6:9]
	v_mfma_f32_16x16x32_bf16 v[2:5], v[184:187], v[200:203], v[2:5]
	v_mfma_f32_16x16x32_bf16 v[114:117], v[176:179], v[208:211], v[114:117]
	v_mfma_f32_16x16x32_bf16 v[118:121], v[184:187], v[208:211], v[118:121]
	v_mfma_f32_16x16x32_bf16 v[122:125], v[176:179], v[216:219], v[122:125]
	v_mfma_f32_16x16x32_bf16 v[126:129], v[184:187], v[216:219], v[126:129]
	v_mfma_f32_16x16x32_bf16 v[14:17], v[180:183], v[196:199], v[14:17]
	v_mfma_f32_16x16x32_bf16 v[10:13], v[188:191], v[196:199], v[10:13]
	v_mfma_f32_16x16x32_bf16 v[6:9], v[180:183], v[204:207], v[6:9]
	v_mfma_f32_16x16x32_bf16 v[2:5], v[188:191], v[204:207], v[2:5]
	v_mfma_f32_16x16x32_bf16 v[114:117], v[180:183], v[212:215], v[114:117]
	v_mfma_f32_16x16x32_bf16 v[118:121], v[188:191], v[212:215], v[118:121]
	v_mfma_f32_16x16x32_bf16 v[122:125], v[180:183], v[220:223], v[122:125]
	v_mfma_f32_16x16x32_bf16 v[126:129], v[188:191], v[220:223], v[126:129]
	s_barrier
	s_add_i32 s59, s59, 2
	s_add_u32 s74, s74, 0x100
	s_addc_u32 s75, s75, 0
	s_cmp_gt_u32 s59, 13
	s_cbranch_scc0 .LBB0_538
	s_branch .Lmy_kexit_2
.LBB0_538:
	v_add_u32_e32 v154, s88, v159
	v_add_u32_e32 v237, s88, v239
	ds_read_b128 v[150:153], v154
	ds_read_b128 v[164:167], v237
	ds_read_b128 v[168:171], v154 offset:2048
	ds_read_b128 v[172:175], v237 offset:2048
	v_add_u32_e32 v154, s89, v159
	v_add_u32_e32 v237, s89, v239
	s_add_u32 s69, s38, s74
	ds_read_b128 v[176:179], v154
	ds_read_b128 v[180:183], v237
	ds_read_b128 v[184:187], v154 offset:2048
	ds_read_b128 v[188:191], v237 offset:2048
	s_addc_u32 s76, s39, s75
	s_add_u32 s69, s69, 0x100
	s_addc_u32 s76, s76, 0
	s_add_u32 s91, s54, s74
	s_addc_u32 s77, s55, s75
	s_cmpk_eq_i32 s74, 0x700
	s_cselect_b32 s79, s56, s76
	s_cselect_b32 s78, s57, s69
	s_cselect_b32 s77, s41, s77
	s_cselect_b32 s76, s58, s91
	v_lshl_add_u64 v[154:155], v[146:147], 0, s[74:75]
	s_add_i32 m0, s15, 0xc000
	ds_read_b128 v[192:195], v162
	ds_read_b128 v[196:199], v238
	ds_read_b128 v[200:203], v162 offset:2048
	ds_read_b128 v[204:207], v238 offset:2048
	ds_read_b128 v[208:211], v162 offset:4096
	ds_read_b128 v[212:215], v238 offset:4096
	ds_read_b128 v[216:219], v162 offset:6144
	ds_read_b128 v[220:223], v238 offset:6144
	global_load_lds_dwordx4 v[154:155], off
	v_lshl_add_u64 v[154:155], v[148:149], 0, s[74:75]
	s_add_i32 m0, s15, 0xe000
	s_nop 0
	global_load_lds_dwordx4 v[154:155], off
	s_waitcnt vmcnt(8)
	s_waitcnt lgkmcnt(0)
	s_barrier
; #define PG8_STAGEA(bufoff, gbase) PG8_STAGE_(bufoff, gbase, voffA)
; #define PG8_STAGEB(bufoff, gbase) PG8_STAGE_(bufoff, gbase, voffB)
; #define PG8_LDA(dst, b, h) do { _Pragma("unroll") for (int m = 0; m < 4; ++m) _Pragma("unroll") for (int k = 0; k < 2; ++k) dst[m][k] = *(const LAS bf16x8*)(lds + PG8_SA(b, h) + aoff + m * 2048 + k * 1024); } while (0)
; #define PG8_LDB(dst, b, h) do { _Pragma("unroll") for (int n = 0; n < 2; ++n) _Pragma("unroll") for (int k = 0; k < 2; ++k) dst[n][k] = *(const LAS bf16x8*)(lds + PG8_SB(b, h) + boff + n * 2048 + k * 1024); } while (0)
; #define PG8_MMA(ai, bj, At, Bt_) do { __builtin_amdgcn_s_setprio(1); _Pragma("unroll") for (int m = 0; m < 4; ++m) _Pragma("unroll") for (int n = 0; n < 2; ++n) _Pragma("unroll") for (int k = 0; k < 2; ++k) \
;         acc[ai][bj][m][n] = __builtin_amdgcn_mfma_f32_16x16x32_bf16(Bt_[n][k], At[m][k], acc[ai][bj][m][n], 0, 0, 0); __builtin_amdgcn_s_setprio(0); } while (0)
; #define PG8_WAIT_V(n) asm volatile("s_waitcnt vmcnt(" #n ")" ::: "memory")
; #define PG8_WAIT_L(n) asm volatile("s_waitcnt lgkmcnt(" #n ")" ::: "memory")
; #define PG8_BAR __builtin_amdgcn_s_barrier()
; #define PG8_SCHED __builtin_amdgcn_sched_barrier(0)
; template <int EK, int SK = -1>
; __device__ __forceinline__ void gemm_phase(LAS unsigned char* lds, const bf16_t* A, const bf16_t* Bt, int nM, int N, int K, const EpiArgs& E) {
;     ...
;             PG8_WAIT_V(8); PG8_WAIT_L(0); PG8_BAR; PG8_MMA(0, 0, At, B0); PG8_MMA(0, 1, At, B1); PG8_BAR; PG8_SCHED;
;             PG8_LDA(At, 0, 1); PG8_STAGEB(PG8_SB(0, 0), b2); PG8_STAGEB(PG8_SB(0, 1), b2 + hstep); PG8_STAGEA(PG8_SA(0, 0), a2);
;             PG8_WAIT_V(8); PG8_WAIT_L(0); PG8_BAR; PG8_MMA(1, 0, At, B0); PG8_MMA(1, 1, At, B1); PG8_BAR; PG8_SCHED;
;             PG8_LDB(B0, 1, 0); PG8_LDB(B1, 1, 1); PG8_SCHED; PG8_LDA(At, 1, 0); PG8_STAGEA(PG8_SA(0, 1), a2 + hstep);
;             PG8_WAIT_V(8); PG8_WAIT_L(0); PG8_BAR; PG8_MMA(0, 0, At, B0); PG8_MMA(0, 1, At, B1); PG8_BAR; PG8_SCHED;
	s_waitcnt lgkmcnt(0)
	v_mfma_f32_16x16x32_bf16 v[110:113], v[150:153], v[192:195], v[110:113]
	v_mfma_f32_16x16x32_bf16 v[106:109], v[168:171], v[192:195], v[106:109]
	v_mfma_f32_16x16x32_bf16 v[102:105], v[150:153], v[200:203], v[102:105]
	v_mfma_f32_16x16x32_bf16 v[98:101], v[168:171], v[200:203], v[98:101]
	v_mfma_f32_16x16x32_bf16 v[94:97], v[150:153], v[208:211], v[94:97]
	v_mfma_f32_16x16x32_bf16 v[90:93], v[168:171], v[208:211], v[90:93]
	v_mfma_f32_16x16x32_bf16 v[86:89], v[150:153], v[216:219], v[86:89]
	v_mfma_f32_16x16x32_bf16 v[82:85], v[168:171], v[216:219], v[82:85]
	v_mfma_f32_16x16x32_bf16 v[110:113], v[164:167], v[196:199], v[110:113]
	v_mfma_f32_16x16x32_bf16 v[106:109], v[172:175], v[196:199], v[106:109]
	v_mfma_f32_16x16x32_bf16 v[102:105], v[164:167], v[204:207], v[102:105]
	v_mfma_f32_16x16x32_bf16 v[98:101], v[172:175], v[204:207], v[98:101]
	v_mfma_f32_16x16x32_bf16 v[94:97], v[164:167], v[212:215], v[94:97]
	v_mfma_f32_16x16x32_bf16 v[90:93], v[172:175], v[212:215], v[90:93]
	v_mfma_f32_16x16x32_bf16 v[86:89], v[164:167], v[220:223], v[86:89]
	v_mfma_f32_16x16x32_bf16 v[82:85], v[172:175], v[220:223], v[82:85]
	v_mfma_f32_16x16x32_bf16 v[78:81], v[176:179], v[192:195], v[78:81]
	v_mfma_f32_16x16x32_bf16 v[74:77], v[184:187], v[192:195], v[74:77]
	v_mfma_f32_16x16x32_bf16 v[70:73], v[176:179], v[200:203], v[70:73]
	v_mfma_f32_16x16x32_bf16 v[66:69], v[184:187], v[200:203], v[66:69]
	v_mfma_f32_16x16x32_bf16 v[62:65], v[176:179], v[208:211], v[62:65]
	v_mfma_f32_16x16x32_bf16 v[58:61], v[184:187], v[208:211], v[58:61]
	v_mfma_f32_16x16x32_bf16 v[54:57], v[176:179], v[216:219], v[54:57]
	v_mfma_f32_16x16x32_bf16 v[50:53], v[184:187], v[216:219], v[50:53]
	v_mfma_f32_16x16x32_bf16 v[78:81], v[180:183], v[196:199], v[78:81]
	v_mfma_f32_16x16x32_bf16 v[74:77], v[188:191], v[196:199], v[74:77]
	v_mfma_f32_16x16x32_bf16 v[70:73], v[180:183], v[204:207], v[70:73]
	v_mfma_f32_16x16x32_bf16 v[66:69], v[188:191], v[204:207], v[66:69]
	v_mfma_f32_16x16x32_bf16 v[62:65], v[180:183], v[212:215], v[62:65]
	v_mfma_f32_16x16x32_bf16 v[58:61], v[188:191], v[212:215], v[58:61]
	v_mfma_f32_16x16x32_bf16 v[54:57], v[180:183], v[220:223], v[54:57]
	v_mfma_f32_16x16x32_bf16 v[50:53], v[188:191], v[220:223], v[50:53]
	s_barrier
	s_add_i32 s69, s88, s83
	v_lshl_add_u64 v[154:155], s[76:77], 0, v[132:133]
	s_mov_b32 m0, s69
	ds_read_b128 v[192:195], v162 offset:16384
	ds_read_b128 v[196:199], v238 offset:16384
	ds_read_b128 v[200:203], v162 offset:18432
	ds_read_b128 v[204:207], v238 offset:18432
	ds_read_b128 v[208:211], v162 offset:20480
	ds_read_b128 v[212:215], v238 offset:20480
	ds_read_b128 v[216:219], v162 offset:22528
	ds_read_b128 v[220:223], v238 offset:22528
	global_load_lds_dwordx4 v[154:155], off
	s_add_i32 m0, s69, 0x2000
	s_add_u32 s92, s76, 0x40000
	v_lshl_add_u64 v[224:225], s[76:77], 0, v[136:137]
	s_addc_u32 s93, s77, 0
	s_add_i32 s69, s89, s83
	global_load_lds_dwordx4 v[224:225], off
	v_lshl_add_u64 v[226:227], s[92:93], 0, v[132:133]
	s_mov_b32 m0, s69
	v_lshl_add_u64 v[228:229], s[78:79], 0, v[134:135]
	global_load_lds_dwordx4 v[226:227], off
	v_lshl_add_u64 v[226:227], s[92:93], 0, v[136:137]
	s_add_i32 m0, s69, 0x2000
	s_nop 0
	global_load_lds_dwordx4 v[226:227], off
	v_lshl_add_u64 v[226:227], s[78:79], 0, v[130:131]
	s_mov_b32 m0, s15
	s_nop 0
	global_load_lds_dwordx4 v[226:227], off
	s_mov_b32 m0, s17
	s_nop 0
	global_load_lds_dwordx4 v[228:229], off
	s_waitcnt vmcnt(8)
	s_waitcnt lgkmcnt(0)
	s_barrier
	s_waitcnt lgkmcnt(0)
	v_mfma_f32_16x16x32_bf16 v[46:49], v[150:153], v[192:195], v[46:49]
	v_mfma_f32_16x16x32_bf16 v[42:45], v[168:171], v[192:195], v[42:45]
	v_mfma_f32_16x16x32_bf16 v[38:41], v[150:153], v[200:203], v[38:41]
	v_mfma_f32_16x16x32_bf16 v[34:37], v[168:171], v[200:203], v[34:37]
	v_mfma_f32_16x16x32_bf16 v[30:33], v[150:153], v[208:211], v[30:33]
	v_mfma_f32_16x16x32_bf16 v[26:29], v[168:171], v[208:211], v[26:29]
	v_mfma_f32_16x16x32_bf16 v[22:25], v[150:153], v[216:219], v[22:25]
	v_mfma_f32_16x16x32_bf16 v[18:21], v[168:171], v[216:219], v[18:21]
	v_mfma_f32_16x16x32_bf16 v[46:49], v[164:167], v[196:199], v[46:49]
	v_mfma_f32_16x16x32_bf16 v[42:45], v[172:175], v[196:199], v[42:45]
	v_mfma_f32_16x16x32_bf16 v[38:41], v[164:167], v[204:207], v[38:41]
	v_mfma_f32_16x16x32_bf16 v[34:37], v[172:175], v[204:207], v[34:37]
	v_mfma_f32_16x16x32_bf16 v[30:33], v[164:167], v[212:215], v[30:33]
	v_mfma_f32_16x16x32_bf16 v[26:29], v[172:175], v[212:215], v[26:29]
	v_mfma_f32_16x16x32_bf16 v[22:25], v[164:167], v[220:223], v[22:25]
	v_mfma_f32_16x16x32_bf16 v[18:21], v[172:175], v[220:223], v[18:21]
	v_mfma_f32_16x16x32_bf16 v[14:17], v[176:179], v[192:195], v[14:17]
	v_mfma_f32_16x16x32_bf16 v[10:13], v[184:187], v[192:195], v[10:13]
	v_mfma_f32_16x16x32_bf16 v[6:9], v[176:179], v[200:203], v[6:9]
	v_mfma_f32_16x16x32_bf16 v[2:5], v[184:187], v[200:203], v[2:5]
	v_mfma_f32_16x16x32_bf16 v[114:117], v[176:179], v[208:211], v[114:117]
	v_mfma_f32_16x16x32_bf16 v[118:121], v[184:187], v[208:211], v[118:121]
	v_mfma_f32_16x16x32_bf16 v[122:125], v[176:179], v[216:219], v[122:125]
	v_mfma_f32_16x16x32_bf16 v[126:129], v[184:187], v[216:219], v[126:129]
	v_mfma_f32_16x16x32_bf16 v[14:17], v[180:183], v[196:199], v[14:17]
	v_mfma_f32_16x16x32_bf16 v[10:13], v[188:191], v[196:199], v[10:13]
	v_mfma_f32_16x16x32_bf16 v[6:9], v[180:183], v[204:207], v[6:9]
	v_mfma_f32_16x16x32_bf16 v[2:5], v[188:191], v[204:207], v[2:5]
	v_mfma_f32_16x16x32_bf16 v[114:117], v[180:183], v[212:215], v[114:117]
	v_mfma_f32_16x16x32_bf16 v[118:121], v[188:191], v[212:215], v[118:121]
	v_mfma_f32_16x16x32_bf16 v[122:125], v[180:183], v[220:223], v[122:125]
	v_mfma_f32_16x16x32_bf16 v[126:129], v[188:191], v[220:223], v[126:129]
	s_barrier
; #define PG8_STAGEA(bufoff, gbase) PG8_STAGE_(bufoff, gbase, voffA)
; #define PG8_STAGEB(bufoff, gbase) PG8_STAGE_(bufoff, gbase, voffB)
; #define PG8_LDA(dst, b, h) do { _Pragma("unroll") for (int m = 0; m < 4; ++m) _Pragma("unroll") for (int k = 0; k < 2; ++k) dst[m][k] = *(const LAS bf16x8*)(lds + PG8_SA(b, h) + aoff + m * 2048 + k * 1024); } while (0)
; #define PG8_MMA(ai, bj, At, Bt_) do { __builtin_amdgcn_s_setprio(1); _Pragma("unroll") for (int m = 0; m < 4; ++m) _Pragma("unroll") for (int n = 0; n < 2; ++n) _Pragma("unroll") for (int k = 0; k < 2; ++k) \
;         acc[ai][bj][m][n] = __builtin_amdgcn_mfma_f32_16x16x32_bf16(Bt_[n][k], At[m][k], acc[ai][bj][m][n], 0, 0, 0); __builtin_amdgcn_s_setprio(0); } while (0)
; #define PG8_WAIT_V(n) asm volatile("s_waitcnt vmcnt(" #n ")" ::: "memory")
; #define PG8_WAIT_L(n) asm volatile("s_waitcnt lgkmcnt(" #n ")" ::: "memory")
; #define PG8_BAR __builtin_amdgcn_s_barrier()
; #define PG8_SCHED __builtin_amdgcn_sched_barrier(0)
; template <int EK, int SK = -1>
; __device__ __forceinline__ void gemm_phase(LAS unsigned char* lds, const bf16_t* A, const bf16_t* Bt, int nM, int N, int K, const EpiArgs& E) {
;     ...
;             PG8_WAIT_V(8); PG8_WAIT_L(0); PG8_BAR; PG8_MMA(0, 0, At, B0); PG8_MMA(0, 1, At, B1); PG8_BAR; PG8_SCHED;
;             PG8_LDA(At, 1, 1); PG8_STAGEB(PG8_SB(1, 0), b3); PG8_STAGEB(PG8_SB(1, 1), b3 + hstep); PG8_STAGEA(PG8_SA(1, 0), a3);
;             PG8_WAIT_V(8); PG8_WAIT_L(0); PG8_BAR; PG8_MMA(1, 0, At, B0); PG8_MMA(1, 1, At, B1); PG8_BAR; PG8_SCHED;
;         }
	s_add_i32 s69, 0, 0x18000
	v_add_u32_e32 v163, s69, v159
	v_add_u32_e32 v236, s69, v239
	s_add_i32 s91, 0, 0x1c000
	ds_read_b128 v[150:153], v163
	ds_read_b128 v[164:167], v236
	ds_read_b128 v[168:171], v163 offset:2048
	ds_read_b128 v[172:175], v236 offset:2048
	v_add_u32_e32 v163, s91, v159
	v_add_u32_e32 v236, s91, v239
	ds_read_b128 v[176:179], v163
	ds_read_b128 v[180:183], v236
	ds_read_b128 v[184:187], v163 offset:2048
	ds_read_b128 v[188:191], v236 offset:2048
	s_add_u32 s78, s78, 0x40000
	s_addc_u32 s79, s79, 0
	s_mov_b32 m0, s84
	v_lshl_add_u64 v[230:231], s[78:79], 0, v[130:131]
	ds_read_b128 v[192:195], v162 offset:32768
	ds_read_b128 v[196:199], v238 offset:32768
	ds_read_b128 v[200:203], v162 offset:34816
	ds_read_b128 v[204:207], v238 offset:34816
	ds_read_b128 v[208:211], v162 offset:36864
	ds_read_b128 v[212:215], v238 offset:36864
	ds_read_b128 v[216:219], v162 offset:38912
	ds_read_b128 v[220:223], v238 offset:38912
	global_load_lds_dwordx4 v[230:231], off
	v_lshl_add_u64 v[230:231], s[78:79], 0, v[134:135]
	s_mov_b32 m0, s85
	s_nop 0
	global_load_lds_dwordx4 v[230:231], off
	s_waitcnt vmcnt(8)
	s_waitcnt lgkmcnt(0)
	s_barrier
	s_waitcnt lgkmcnt(0)
	v_mfma_f32_16x16x32_bf16 v[110:113], v[150:153], v[192:195], v[110:113]
	v_mfma_f32_16x16x32_bf16 v[106:109], v[168:171], v[192:195], v[106:109]
	v_mfma_f32_16x16x32_bf16 v[102:105], v[150:153], v[200:203], v[102:105]
	v_mfma_f32_16x16x32_bf16 v[98:101], v[168:171], v[200:203], v[98:101]
	v_mfma_f32_16x16x32_bf16 v[94:97], v[150:153], v[208:211], v[94:97]
	v_mfma_f32_16x16x32_bf16 v[90:93], v[168:171], v[208:211], v[90:93]
	v_mfma_f32_16x16x32_bf16 v[86:89], v[150:153], v[216:219], v[86:89]
	v_mfma_f32_16x16x32_bf16 v[82:85], v[168:171], v[216:219], v[82:85]
	v_mfma_f32_16x16x32_bf16 v[110:113], v[164:167], v[196:199], v[110:113]
	v_mfma_f32_16x16x32_bf16 v[106:109], v[172:175], v[196:199], v[106:109]
	v_mfma_f32_16x16x32_bf16 v[102:105], v[164:167], v[204:207], v[102:105]
	v_mfma_f32_16x16x32_bf16 v[98:101], v[172:175], v[204:207], v[98:101]
	v_mfma_f32_16x16x32_bf16 v[94:97], v[164:167], v[212:215], v[94:97]
	v_mfma_f32_16x16x32_bf16 v[90:93], v[172:175], v[212:215], v[90:93]
	v_mfma_f32_16x16x32_bf16 v[86:89], v[164:167], v[220:223], v[86:89]
	v_mfma_f32_16x16x32_bf16 v[82:85], v[172:175], v[220:223], v[82:85]
	v_mfma_f32_16x16x32_bf16 v[78:81], v[176:179], v[192:195], v[78:81]
	v_mfma_f32_16x16x32_bf16 v[74:77], v[184:187], v[192:195], v[74:77]
	v_mfma_f32_16x16x32_bf16 v[70:73], v[176:179], v[200:203], v[70:73]
	v_mfma_f32_16x16x32_bf16 v[66:69], v[184:187], v[200:203], v[66:69]
	v_mfma_f32_16x16x32_bf16 v[62:65], v[176:179], v[208:211], v[62:65]
	v_mfma_f32_16x16x32_bf16 v[58:61], v[184:187], v[208:211], v[58:61]
	v_mfma_f32_16x16x32_bf16 v[54:57], v[176:179], v[216:219], v[54:57]
	v_mfma_f32_16x16x32_bf16 v[50:53], v[184:187], v[216:219], v[50:53]
	v_mfma_f32_16x16x32_bf16 v[78:81], v[180:183], v[196:199], v[78:81]
	v_mfma_f32_16x16x32_bf16 v[74:77], v[188:191], v[196:199], v[74:77]
	v_mfma_f32_16x16x32_bf16 v[70:73], v[180:183], v[204:207], v[70:73]
	v_mfma_f32_16x16x32_bf16 v[66:69], v[188:191], v[204:207], v[66:69]
	v_mfma_f32_16x16x32_bf16 v[62:65], v[180:183], v[212:215], v[62:65]
	v_mfma_f32_16x16x32_bf16 v[58:61], v[188:191], v[212:215], v[58:61]
	v_mfma_f32_16x16x32_bf16 v[54:57], v[180:183], v[220:223], v[54:57]
	v_mfma_f32_16x16x32_bf16 v[50:53], v[188:191], v[220:223], v[50:53]
	s_barrier
	s_add_i32 s69, s69, s83
	v_lshl_add_u64 v[154:155], v[154:155], 0, s[10:11]
	s_mov_b32 m0, s69
	ds_read_b128 v[192:195], v162 offset:49152
	ds_read_b128 v[196:199], v238 offset:49152
	ds_read_b128 v[200:203], v162 offset:51200
	ds_read_b128 v[204:207], v238 offset:51200
	ds_read_b128 v[208:211], v162 offset:53248
	ds_read_b128 v[212:215], v238 offset:53248
	ds_read_b128 v[216:219], v162 offset:55296
	ds_read_b128 v[220:223], v238 offset:55296
	global_load_lds_dwordx4 v[154:155], off
	s_add_i32 m0, s69, 0x2000
	s_add_u32 s76, s76, 0x40080
	v_lshl_add_u64 v[154:155], v[224:225], 0, s[10:11]
	s_addc_u32 s77, s77, 0
	s_add_i32 s69, s91, s83
	global_load_lds_dwordx4 v[154:155], off
	v_lshl_add_u64 v[154:155], s[76:77], 0, v[132:133]
	s_mov_b32 m0, s69
	s_nop 0
	global_load_lds_dwordx4 v[154:155], off
	v_lshl_add_u64 v[154:155], s[76:77], 0, v[136:137]
	s_add_i32 m0, s69, 0x2000
	s_nop 0
	global_load_lds_dwordx4 v[154:155], off
	v_lshl_add_u64 v[154:155], v[226:227], 0, s[10:11]
	s_mov_b32 m0, s86
	s_nop 0
	global_load_lds_dwordx4 v[154:155], off
	v_lshl_add_u64 v[154:155], v[228:229], 0, s[10:11]
	s_mov_b32 m0, s87
	s_nop 0
	global_load_lds_dwordx4 v[154:155], off
	s_waitcnt vmcnt(8)
	s_waitcnt lgkmcnt(0)
	s_barrier
	s_waitcnt lgkmcnt(0)
	v_mfma_f32_16x16x32_bf16 v[46:49], v[150:153], v[192:195], v[46:49]
	v_mfma_f32_16x16x32_bf16 v[42:45], v[168:171], v[192:195], v[42:45]
	v_mfma_f32_16x16x32_bf16 v[38:41], v[150:153], v[200:203], v[38:41]
	v_mfma_f32_16x16x32_bf16 v[34:37], v[168:171], v[200:203], v[34:37]
	v_mfma_f32_16x16x32_bf16 v[30:33], v[150:153], v[208:211], v[30:33]
	v_mfma_f32_16x16x32_bf16 v[26:29], v[168:171], v[208:211], v[26:29]
	v_mfma_f32_16x16x32_bf16 v[22:25], v[150:153], v[216:219], v[22:25]
	v_mfma_f32_16x16x32_bf16 v[18:21], v[168:171], v[216:219], v[18:21]
	v_mfma_f32_16x16x32_bf16 v[46:49], v[164:167], v[196:199], v[46:49]
	v_mfma_f32_16x16x32_bf16 v[42:45], v[172:175], v[196:199], v[42:45]
	v_mfma_f32_16x16x32_bf16 v[38:41], v[164:167], v[204:207], v[38:41]
	v_mfma_f32_16x16x32_bf16 v[34:37], v[172:175], v[204:207], v[34:37]
	v_mfma_f32_16x16x32_bf16 v[30:33], v[164:167], v[212:215], v[30:33]
	v_mfma_f32_16x16x32_bf16 v[26:29], v[172:175], v[212:215], v[26:29]
	v_mfma_f32_16x16x32_bf16 v[22:25], v[164:167], v[220:223], v[22:25]
	v_mfma_f32_16x16x32_bf16 v[18:21], v[172:175], v[220:223], v[18:21]
	v_mfma_f32_16x16x32_bf16 v[14:17], v[176:179], v[192:195], v[14:17]
	v_mfma_f32_16x16x32_bf16 v[10:13], v[184:187], v[192:195], v[10:13]
	v_mfma_f32_16x16x32_bf16 v[6:9], v[176:179], v[200:203], v[6:9]
	v_mfma_f32_16x16x32_bf16 v[2:5], v[184:187], v[200:203], v[2:5]
	v_mfma_f32_16x16x32_bf16 v[114:117], v[176:179], v[208:211], v[114:117]
	v_mfma_f32_16x16x32_bf16 v[118:121], v[184:187], v[208:211], v[118:121]
	v_mfma_f32_16x16x32_bf16 v[122:125], v[176:179], v[216:219], v[122:125]
	v_mfma_f32_16x16x32_bf16 v[126:129], v[184:187], v[216:219], v[126:129]
	v_mfma_f32_16x16x32_bf16 v[14:17], v[180:183], v[196:199], v[14:17]
	v_mfma_f32_16x16x32_bf16 v[10:13], v[188:191], v[196:199], v[10:13]
	v_mfma_f32_16x16x32_bf16 v[6:9], v[180:183], v[204:207], v[6:9]
	v_mfma_f32_16x16x32_bf16 v[2:5], v[188:191], v[204:207], v[2:5]
	v_mfma_f32_16x16x32_bf16 v[114:117], v[180:183], v[212:215], v[114:117]
	v_mfma_f32_16x16x32_bf16 v[118:121], v[188:191], v[212:215], v[118:121]
	v_mfma_f32_16x16x32_bf16 v[122:125], v[180:183], v[220:223], v[122:125]
	v_mfma_f32_16x16x32_bf16 v[126:129], v[188:191], v[220:223], v[126:129]
	s_barrier
	s_add_i32 s59, s59, 2
	s_add_u32 s74, s74, 0x100
	s_addc_u32 s75, s75, 0
	s_cmp_gt_u32 s59, 13
	s_cbranch_scc0 .LBB0_538

; #define LAS __attribute__((address_space(3)))
; #define PG8_STAGEA(bufoff, gbase) PG8_STAGE_(bufoff, gbase, voffA)
; #define PG8_STAGEB(bufoff, gbase) PG8_STAGE_(bufoff, gbase, voffB)
; template <int EK, int SK = -1>
; __device__ __forceinline__ void gemm_phase(LAS unsigned char* lds, const bf16_t* A, const bf16_t* Bt, int nM, int N, int K, const EpiArgs& E) {
;     const int tid = threadIdx.x, wid = __builtin_amdgcn_readfirstlane(tid >> 6), lane = tid & 63, wr = wid >> 2, wc = wid & 3, fr = lane & 15, fq = lane >> 4;
;     const int nt = K / BK;
;     SOrder S; S.init(nM, N, (int)gridDim.x, (int)blockIdx.x);
;     LAS float* rtab = (LAS float*)(lds + RTAB_OFF);
;     unsigned voffA[2], voffB[2];
; #pragma unroll
;     for (int i = 0; i < 2; ++i) { int R, C; stage_rc(tid * 16 + i * 8192, R, C); const int Rb = (R & ~31) + perm32(R & 31);
;         voffA[i] = (unsigned)(R * K + C) * 2u; voffB[i] = (unsigned)(Rb * K + C) * 2u; }
;     const size_t kstep = (size_t)(BK * 2);
;     const size_t hstep = (size_t)HALF * K * 2;
;     const size_t tstep = 2 * hstep;
;     const unsigned ldsw = (unsigned)wid * 1024u;
;     const int aoff = lds_byte(wr * 64 + fr, fq * 8), boff = lds_byte(wc * 32 + fr, fq * 8);
;     ...
;     Unit cur, nxt; int ui = 0;
;     if (!S.next(0, cur)) { if (SK >= 0) skinny_phase<(SK >= 0 ? SK : 0)>(lds + 32768, (LAS float*)(lds + SRED_OFF), A, Bt, N, K, E); return; }
;     f32x4 acc[2][2][4][2];
; #pragma unroll
;     for (int a = 0; a < 2; ++a)
; #pragma unroll
;         for (int b = 0; b < 2; ++b)
; #pragma unroll
;             for (int m = 0; m < 4; ++m)
; #pragma unroll
;                 for (int n = 0; n < 2; ++n) acc[a][b][m][n] = (f32x4){0.f, 0.f, 0.f, 0.f};
;     bf16x8 At[4][2], B0[2][2], B1[2][2];
;     const char* cA = (const char*)A + (size_t)cur.pm * tstep; const char* cB = (const char*)Bt + (size_t)cur.pn * tstep;
;     PG8_STAGEB(PG8_SB(0, 0), cB); PG8_STAGEB(PG8_SB(0, 1), cB + hstep); PG8_STAGEA(PG8_SA(0, 0), cA); PG8_STAGEA(PG8_SA(0, 1), cA + hstep);
;     f32x4 tq[4][4]; bool okq[4];
;     if (EK != EK_RES && EK != EK_FINAL) {
; #pragma unroll
;         for (int j = 0; j < 4; ++j) { Unit uu; okq[j] = S.next((tid >> 8) + 2 * j, uu);
;             if (okq[j]) { const f32x4* sp = (const f32x4*)(E.stIn + (size_t)(uu.pm * BM + (tid & 255)) * 16); tq[j][0] = sp[0]; tq[j][1] = sp[1]; tq[j][2] = sp[2]; tq[j][3] = sp[3]; } }
.LBB0_1201:
	s_load_dword s46, s[0:1], 0xb8
	s_andn2_b64 vcc, exec, s[4:5]
	s_cbranch_vccnz .LBB0_1253
	s_waitcnt vmcnt(0)
	v_lshrrev_b32_e32 v3, 1, v0
	v_and_b32_e32 v78, 24, v3
	v_lshrrev_b32_e32 v3, 5, v0
	v_lshlrev_b32_e32 v1, 4, v0
	v_and_b32_e32 v2, 32, v0
	v_and_b32_e32 v3, 4, v3
	v_bfe_u32 v4, v0, 2, 2
	v_bfe_u32 v76, v0, 2, 4
	v_bitop3_b32 v74, v1, v2, 48 bitop3:0x6c
	v_and_b32_e32 v75, 64, v0
	v_or3_b32 v3, v3, v4, v78
	v_lshrrev_b32_e32 v4, 3, v0
	v_or_b32_e32 v77, 0x2000, v1
	s_add_u32 s47, s30, 0x1c80000
	v_or_b32_e32 v2, v74, v75
	v_and_or_b32 v5, v4, 48, v76
	v_and_or_b32 v4, v4, 32, v3
	v_lshrrev_b32_e32 v1, 7, v77
	s_movk_i32 s4, 0x70
	s_addc_u32 s48, s31, 0
	v_and_or_b32 v4, v1, s4, v76
	s_movk_i32 s4, 0x60
	s_lshr_b32 s27, s26, 6
	s_ashr_i32 s19, s18, 31
	s_ashr_i32 s17, s16, 31
	v_and_or_b32 v1, v1, s4, v3
	s_lshl_b32 s49, s27, 10
	s_lshl_b64 s[4:5], s[18:19], 19
	s_lshl_b64 s[6:7], s[16:17], 19
	s_add_u32 s40, s47, s6
	s_addc_u32 s41, s48, s7
	s_add_i32 s17, s49, 0
	s_add_i32 m0, s17, 0x10000
	v_lshrrev_b32_e32 v232, 3, v0
	v_xor_b32_e32 v233, v0, v232
	v_and_b32_e32 v233, 7, v233
	v_lshlrev_b32_e32 v233, 4, v233
	v_bfe_u32 v234, v0, 3, 2
	v_bfe_u32 v235, v0, 7, 1
	v_lshl_or_b32 v234, v235, 2, v234
	v_bfe_u32 v235, v0, 5, 1
	v_lshl_or_b32 v234, v235, 3, v234
	v_bfe_u32 v235, v0, 6, 1
	v_lshl_or_b32 v234, v235, 4, v234
	v_bfe_u32 v235, v0, 8, 1
	v_lshl_or_b32 v234, v235, 5, v234
	v_lshl_or_b32 v130, v232, 11, v233
	v_lshl_or_b32 v132, v234, 11, v233
	v_add_u32_e32 v134, 0x20000, v130
	v_add_u32_e32 v136, 0x20000, v132
	global_load_lds_dwordx4 v132, s[40:41]
	s_add_i32 m0, s17, 0x12000
	s_add_u32 s6, s40, 0x40000
	global_load_lds_dwordx4 v136, s[40:41]
	s_addc_u32 s7, s41, 0
	s_add_i32 m0, s17, 0x14000
	global_load_lds_dwordx4 v132, s[6:7]
	s_add_i32 m0, s17, 0x16000
	s_add_u32 s20, s62, s4
	s_addc_u32 s21, s63, s5
	s_add_i32 s19, s17, 0x2000
	global_load_lds_dwordx4 v136, s[6:7]
	s_mov_b32 m0, s17
	s_add_u32 s4, s20, 0x40000
	global_load_lds_dwordx4 v130, s[20:21]
	s_mov_b32 m0, s19
	s_addc_u32 s5, s21, 0
	s_add_i32 s50, s17, 0x4000
	global_load_lds_dwordx4 v134, s[20:21]
	s_mov_b32 m0, s50
	s_add_i32 s51, s17, 0x6000
	global_load_lds_dwordx4 v130, s[4:5]
	s_mov_b32 m0, s51
	v_lshrrev_b32_e32 v50, 8, v0
	global_load_lds_dwordx4 v134, s[4:5]
	v_mov_b64_e32 v[2:3], s[2:3]
	s_waitcnt lgkmcnt(0)
	v_mad_i64_i32 v[2:3], s[4:5], s46, v50, v[2:3]
	v_mov_b32_e32 v133, 0
	s_mov_b64 s[4:5], 0x596
	v_mov_b32_e32 v137, v133
	v_mov_b32_e32 v131, v133
	v_mov_b32_e32 v135, v133
	v_and_b32_e32 v1, 0xff, v0
	v_cmp_gt_i64_e32 vcc, s[4:5], v[2:3]
	s_and_saveexec_b64 s[6:7], vcc
	s_cbranch_execz .LBB0_1208
	v_ashrrev_i32_e32 v3, 31, v2
	v_lshrrev_b32_e32 v3, 29, v3
	v_add_u32_e32 v4, v2, v3
	v_and_b32_e32 v3, -8, v4
	v_sub_u32_e32 v3, v2, v3
	v_cmp_lt_i32_e64 s[4:5], 5, v3
	s_and_saveexec_b64 s[8:9], s[4:5]
	s_xor_b64 s[4:5], exec, s[8:9]
	s_movk_i32 s8, 0xb2
	v_mad_u64_u32 v[2:3], s[8:9], v3, s8, 6
	s_or_saveexec_b64 s[4:5], s[4:5]
	v_ashrrev_i32_e32 v4, 3, v4
	s_xor_b64 exec, exec, s[4:5]
	s_movk_i32 s8, 0xb3
	v_mul_lo_u32 v2, v3, s8
	s_or_b64 exec, exec, s[4:5]
	v_add_u32_e32 v2, v2, v4
	s_mov_b32 s4, 0x2e8ba2e9
	v_mul_hi_i32 v3, v2, s4
	v_lshrrev_b32_e32 v4, 31, v3
	v_ashrrev_i32_e32 v3, 4, v3
	v_add_u32_e32 v3, v3, v4
	v_lshlrev_b32_e32 v4, 2, v3
	v_sub_u32_e32 v5, 0x41, v4
	v_min_i32_e32 v5, 4, v5
	v_sub_u32_e32 v6, 0, v5
	v_max_i32_e32 v5, v5, v6
	v_cvt_f32_u32_e32 v6, v5
	s_movk_i32 s4, 0x58
	v_mul_lo_u32 v3, v3, s4
	v_sub_u32_e32 v2, v2, v3
	v_rcp_iflag_f32_e32 v6, v6
	v_sub_u32_e32 v7, 0, v2
	v_ashrrev_i32_e32 v3, 31, v2
	v_max_i32_e32 v2, v2, v7
	v_mul_f32_e32 v6, 0x4f7ffffe, v6
	v_cvt_u32_f32_e32 v6, v6
	v_sub_u32_e32 v7, 0, v5
	v_mul_lo_u32 v7, v7, v6
	v_mul_hi_u32 v7, v6, v7
	v_add_u32_e32 v6, v6, v7
	v_mul_hi_u32 v6, v2, v6
	v_mul_lo_u32 v6, v6, v5
	v_sub_u32_e32 v2, v2, v6
	v_sub_u32_e32 v6, v2, v5
	v_cmp_ge_u32_e64 s[4:5], v2, v5
	s_nop 1
	v_cndmask_b32_e64 v2, v2, v6, s[4:5]
	v_sub_u32_e32 v6, v2, v5
	v_cmp_ge_u32_e64 s[4:5], v2, v5
	s_nop 1
	v_cndmask_b32_e64 v2, v2, v6, s[4:5]
	v_xor_b32_e32 v2, v2, v3
	v_sub_u32_e32 v2, v2, v3
	v_add_u32_e32 v2, v4, v2
	v_lshl_or_b32 v2, v2, 8, v1
	v_ashrrev_i32_e32 v3, 31, v2
	v_lshlrev_b64 v[2:3], 6, v[2:3]
	v_lshl_add_u64 v[18:19], s[12:13], 0, v[2:3]
	global_load_dwordx4 v[2:5], v[18:19], off offset:48
	global_load_dwordx4 v[10:13], v[18:19], off offset:32
	global_load_dwordx4 v[6:9], v[18:19], off offset:16
	global_load_dwordx4 v[14:17], v[18:19], off

; #define LAS __attribute__((address_space(3)))
; __device__ __forceinline__ float hsum4(f32x4 v) { return (v[0] + v[1]) + (v[2] + v[3]); }
; #define PG8_STAGEA(bufoff, gbase) PG8_STAGE_(bufoff, gbase, voffA)
; #define PG8_STAGEB(bufoff, gbase) PG8_STAGE_(bufoff, gbase, voffB)
; template <int EK, int SK = -1>
; __device__ __forceinline__ void gemm_phase(LAS unsigned char* lds, const bf16_t* A, const bf16_t* Bt, int nM, int N, int K, const EpiArgs& E) {
;     ...
;     const int aoff = lds_byte(wr * 64 + fr, fq * 8), boff = lds_byte(wc * 32 + fr, fq * 8);
;     ...
;     Unit cur, nxt; int ui = 0;
;     if (!S.next(0, cur)) { if (SK >= 0) skinny_phase<(SK >= 0 ? SK : 0)>(lds + 32768, (LAS float*)(lds + SRED_OFF), A, Bt, N, K, E); return; }
;     f32x4 acc[2][2][4][2];
; #pragma unroll
;     for (int a = 0; a < 2; ++a)
; #pragma unroll
;         for (int b = 0; b < 2; ++b)
; #pragma unroll
;             for (int m = 0; m < 4; ++m)
; #pragma unroll
;                 for (int n = 0; n < 2; ++n) acc[a][b][m][n] = (f32x4){0.f, 0.f, 0.f, 0.f};
;     bf16x8 At[4][2], B0[2][2], B1[2][2];
;     const char* cA = (const char*)A + (size_t)cur.pm * tstep; const char* cB = (const char*)Bt + (size_t)cur.pn * tstep;
;     PG8_STAGEB(PG8_SB(0, 0), cB); PG8_STAGEB(PG8_SB(0, 1), cB + hstep); PG8_STAGEA(PG8_SA(0, 0), cA); PG8_STAGEA(PG8_SA(0, 1), cA + hstep);
;     f32x4 tq[4][4]; bool okq[4];
;     if (EK != EK_RES && EK != EK_FINAL) {
; #pragma unroll
;         for (int j = 0; j < 4; ++j) { Unit uu; okq[j] = S.next((tid >> 8) + 2 * j, uu);
;             if (okq[j]) { const f32x4* sp = (const f32x4*)(E.stIn + (size_t)(uu.pm * BM + (tid & 255)) * 16); tq[j][0] = sp[0]; tq[j][1] = sp[1]; tq[j][2] = sp[2]; tq[j][3] = sp[3]; } }
;     }
;     if (SK >= 0) skinny_phase<(SK >= 0 ? SK : 0)>(lds + 32768, (LAS float*)(lds + SRED_OFF), A, Bt, N, K, E);
;     if (EK != EK_RES && EK != EK_FINAL) {
; #pragma unroll
;         for (int j = 0; j < 4; ++j) if (okq[j]) { const float s_ = (hsum4(tq[j][0]) + hsum4(tq[j][1])) + (hsum4(tq[j][2]) + hsum4(tq[j][3]));
;             rtab[((tid >> 8) + 2 * j) * 256 + (tid & 255)] = rsqrtf(s_ * (1.0f / 1024.0f) + EPS); }
;         __syncthreads();
;     }
;     if (wr == 1) PG8_BAR;
;     PG8_WAIT_V(2); PG8_BAR;
;     PG8_STAGEB(PG8_SB(1, 0), cB + kstep); PG8_STAGEA(PG8_SA(1, 0), cA + kstep); PG8_STAGEB(PG8_SB(1, 1), cB + hstep + kstep);
;     PG8_WAIT_V(6); PG8_BAR;
.LBB0_1236:
	v_and_b32_e32 v2, 15, v0
	v_lshlrev_b32_e32 v3, 1, v78
	v_lshlrev_b32_e32 v5, 2, v2
	v_lshl_or_b32 v1, s4, 6, v2
	v_lshl_or_b32 v4, v2, 6, v3
	s_lshl_b32 s5, s4, 13
	v_and_b32_e32 v2, 32, v5
	v_bitop3_b32 v4, v4, s5, v2 bitop3:0xde
	s_lshl_b32 s5, s27, 5
	v_lshlrev_b32_e32 v2, 6, v0
	s_movk_i32 s6, 0x3c0
	s_and_b32 s5, s5, 0x60
	v_and_or_b32 v2, v2, s6, v3
	v_lshlrev_b32_e32 v3, 2, v0
	s_lshl_b32 s6, s5, 7
	v_and_b32_e32 v3, 32, v3
	s_mov_b64 s[10:11], 0x80
	v_and_b32_e32 v232, 15, v0
	v_bfe_u32 v233, v0, 4, 2
	v_and_b32_e32 v234, 7, v232
	v_xor_b32_e32 v233, v233, v234
	v_lshlrev_b32_e32 v233, 4, v233
	v_lshl_or_b32 v233, v234, 7, v233
	v_lshrrev_b32_e32 v232, 3, v232
	v_bfe_u32 v234, v0, 6, 2
	v_lshl_or_b32 v234, v234, 2, v232
	v_lshl_or_b32 v156, v234, 10, v233
	v_xor_b32_e32 v239, 64, v156
	s_add_i32 m0, s17, 0x18000
	v_lshl_add_u64 v[2:3], v[72:73], 0, s[10:11]
	s_waitcnt vmcnt(2)
	s_barrier
	global_load_lds_dwordx4 v[2:3], off
	v_lshl_add_u64 v[2:3], v[70:71], 0, s[10:11]
	s_add_i32 m0, s17, 0x1a000
	s_add_i32 s52, s17, 0x8000
	s_add_i32 s53, s17, 0xa000
	global_load_lds_dwordx4 v[2:3], off
	v_lshl_add_u64 v[2:3], v[68:69], 0, s[10:11]
	s_mov_b32 m0, s52
	s_add_u32 s12, s40, 0x40080
	global_load_lds_dwordx4 v[2:3], off
	v_lshl_add_u64 v[2:3], v[66:67], 0, s[10:11]
	s_mov_b32 m0, s53
	s_addc_u32 s13, s41, 0
	global_load_lds_dwordx4 v[2:3], off
	s_add_i32 m0, s17, 0x1c000
	v_lshl_add_u64 v[2:3], s[12:13], 0, v[132:133]
	global_load_lds_dwordx4 v[2:3], off
	v_lshl_add_u64 v[2:3], s[12:13], 0, v[136:137]
	s_add_i32 m0, s17, 0x1e000
	s_lshl_b32 s4, s4, 8
	global_load_lds_dwordx4 v[2:3], off
	s_add_i32 s4, s4, 0
	s_add_i32 s4, s4, 0x20010
	v_lshlrev_b32_e32 v2, 8, v0
	v_add_u32_e32 v157, s4, v5
	v_and_b32_e32 v2, 0x18000, v2
	v_lshlrev_b32_e32 v5, 11, v76
	v_or3_b32 v2, v74, v2, v5
	s_mov_b64 s[6:7], 0x40080
	v_add_u32_e32 v2, v2, v75
	v_mov_b32_e32 v3, 0
	v_lshl_add_u64 v[138:139], v[130:131], 0, s[6:7]
	v_lshlrev_b32_e32 v2, 4, v77
	v_and_b32_e32 v2, 0x38000, v2
	s_waitcnt vmcnt(6)
	v_or3_b32 v2, v74, v2, v5
	s_cmpk_lt_u32 s26, 0x100
	v_add_u32_e32 v2, v2, v75
	s_mov_b32 s57, 0
	s_cselect_b64 s[12:13], -1, 0
	v_or_b32_e32 v158, s5, v78
	v_lshl_add_u64 v[140:141], v[134:135], 0, s[6:7]
	v_mov_b64_e32 v[142:143], 0x596
	v_mov_b64_e32 v[144:145], 0x595
	s_add_i32 s54, 0, 0x10000
	s_add_i32 s55, 0, 0x14000
	v_and_b32_e32 v232, 15, v0
	v_bfe_u32 v233, v0, 4, 2
	v_and_b32_e32 v234, 7, v232
	v_xor_b32_e32 v233, v233, v234
	v_lshlrev_b32_e32 v233, 4, v233
	v_lshl_or_b32 v233, v234, 7, v233
	v_lshrrev_b32_e32 v232, 3, v232
	v_lshrrev_b32_e32 v234, 8, v0
	v_lshl_or_b32 v234, v234, 3, v232
	v_lshl_or_b32 v159, v234, 10, v233
	v_xor_b32_e32 v238, 64, v159
	s_movk_i32 s56, 0x1600
	v_mov_b32_e32 v2, v3
	s_barrier
	s_branch .LBB0_1238

; #define PG8_STAGEA(bufoff, gbase) PG8_STAGE_(bufoff, gbase, voffA)
; #define PG8_STAGEB(bufoff, gbase) PG8_STAGE_(bufoff, gbase, voffB)
; #define PG8_LDA(dst, b, h) do { _Pragma("unroll") for (int m = 0; m < 4; ++m) _Pragma("unroll") for (int k = 0; k < 2; ++k) dst[m][k] = *(const LAS bf16x8*)(lds + PG8_SA(b, h) + aoff + m * 2048 + k * 1024); } while (0)
; #define PG8_LDB(dst, b, h) do { _Pragma("unroll") for (int n = 0; n < 2; ++n) _Pragma("unroll") for (int k = 0; k < 2; ++k) dst[n][k] = *(const LAS bf16x8*)(lds + PG8_SB(b, h) + boff + n * 2048 + k * 1024); } while (0)
; #define PG8_MMA(ai, bj, At, Bt_) do { __builtin_amdgcn_s_setprio(1); _Pragma("unroll") for (int m = 0; m < 4; ++m) _Pragma("unroll") for (int n = 0; n < 2; ++n) _Pragma("unroll") for (int k = 0; k < 2; ++k) \
;         acc[ai][bj][m][n] = __builtin_amdgcn_mfma_f32_16x16x32_bf16(Bt_[n][k], At[m][k], acc[ai][bj][m][n], 0, 0, 0); __builtin_amdgcn_s_setprio(0); } while (0)
; #define PG8_WAIT_V(n) asm volatile("s_waitcnt vmcnt(" #n ")" ::: "memory")
; #define PG8_WAIT_L(n) asm volatile("s_waitcnt lgkmcnt(" #n ")" ::: "memory")
; #define PG8_BAR __builtin_amdgcn_s_barrier()
; template <int EK, int SK = -1>
; __device__ __forceinline__ void gemm_phase(LAS unsigned char* lds, const bf16_t* A, const bf16_t* Bt, int nM, int N, int K, const EpiArgs& E) {
;     ...
;         const bool has_next = S.next(ui + 1, nxt);
;         const char* nA = has_next ? (const char*)A + (size_t)nxt.pm * tstep : cA; const char* nB = has_next ? (const char*)Bt + (size_t)nxt.pn * tstep : cB;
;         for (int t = 0; t < nt; t += 2) {
;             const bool last = (t == nt - 2);
;             const char* a1 = cA + (size_t)(t + 1) * kstep;
;             const char* a2 = last ? nA : cA + (size_t)(t + 2) * kstep; const char* b2 = last ? nB : cB + (size_t)(t + 2) * kstep;
;             const char* a3 = a2 + kstep; const char* b3 = b2 + kstep;
;             PG8_LDB(B0, 0, 0); PG8_LDB(B1, 0, 1); PG8_SCHED; PG8_LDA(At, 0, 0); PG8_STAGEA(PG8_SA(1, 1), a1 + hstep);
;             PG8_WAIT_V(8); PG8_WAIT_L(0); PG8_BAR; PG8_MMA(0, 0, At, B0); PG8_MMA(0, 1, At, B1); PG8_BAR; PG8_SCHED;
;             PG8_LDA(At, 0, 1); PG8_STAGEB(PG8_SB(0, 0), b2); PG8_STAGEB(PG8_SB(0, 1), b2 + hstep); PG8_STAGEA(PG8_SA(0, 0), a2);
;             PG8_WAIT_V(8); PG8_WAIT_L(0); PG8_BAR; PG8_MMA(1, 0, At, B0); PG8_MMA(1, 1, At, B1); PG8_BAR; PG8_SCHED;
.LBB0_1244:
	s_add_u32 s59, s40, 0x100
	s_addc_u32 s66, s41, 0
	s_ashr_i32 s27, s26, 31
	s_lshl_b64 s[36:37], s[26:27], 19
	s_add_u32 s38, s62, s36
	s_addc_u32 s39, s63, s37
	s_and_b64 s[36:37], s[6:7], exec
	s_cselect_b32 s27, s39, s21
	s_cselect_b32 s67, s38, s20
	s_ashr_i32 s23, s22, 31
	s_lshl_b64 s[36:37], s[22:23], 19
	s_add_u32 s36, s47, s36
	s_addc_u32 s37, s48, s37
	s_and_b64 s[42:43], s[6:7], exec
	s_cselect_b32 s23, s37, s41
	s_cselect_b32 s68, s36, s40
	v_lshl_add_u64 v[146:147], s[20:21], 0, v[138:139]
	v_lshl_add_u64 v[148:149], s[20:21], 0, v[140:141]
	s_mov_b32 s69, -2
	s_mov_b64 s[40:41], 0
	v_add_u32_e32 v154, s54, v156
	v_add_u32_e32 v237, s54, v239
	ds_read_b128 v[150:153], v154
	ds_read_b128 v[160:163], v237
	ds_read_b128 v[164:167], v154 offset:2048
	ds_read_b128 v[168:171], v237 offset:2048
	v_add_u32_e32 v154, s55, v156
	v_add_u32_e32 v237, s55, v239
	s_add_u32 s42, s20, s40
	ds_read_b128 v[172:175], v154
	ds_read_b128 v[176:179], v237
	ds_read_b128 v[180:183], v154 offset:2048
	ds_read_b128 v[184:187], v237 offset:2048
	s_addc_u32 s43, s21, s41
	s_add_u32 s42, s42, 0x100
	s_addc_u32 s43, s43, 0
	s_add_u32 s70, s59, s40
	s_addc_u32 s71, s66, s41
	s_cmpk_eq_i32 s40, 0x700
	s_cselect_b32 s45, s27, s43
	s_cselect_b32 s44, s67, s42
	s_cselect_b32 s43, s23, s71
	s_cselect_b32 s42, s68, s70
	v_lshl_add_u64 v[154:155], v[146:147], 0, s[40:41]
	s_add_i32 m0, s17, 0xc000
	ds_read_b128 v[188:191], v159
	ds_read_b128 v[192:195], v238
	ds_read_b128 v[196:199], v159 offset:2048
	ds_read_b128 v[200:203], v238 offset:2048
	ds_read_b128 v[204:207], v159 offset:4096
	ds_read_b128 v[208:211], v238 offset:4096
	ds_read_b128 v[212:215], v159 offset:6144
	ds_read_b128 v[216:219], v238 offset:6144
	global_load_lds_dwordx4 v[154:155], off
	v_lshl_add_u64 v[154:155], v[148:149], 0, s[40:41]
	s_add_i32 m0, s17, 0xe000
	s_nop 0
	global_load_lds_dwordx4 v[154:155], off
	s_waitcnt vmcnt(8)
	s_waitcnt lgkmcnt(0)
	s_barrier
	s_waitcnt lgkmcnt(0)
	v_mfma_f32_16x16x32_bf16 v[110:113], v[150:153], v[188:191], 0
	v_mfma_f32_16x16x32_bf16 v[106:109], v[164:167], v[188:191], 0
	v_mfma_f32_16x16x32_bf16 v[102:105], v[150:153], v[196:199], 0
	v_mfma_f32_16x16x32_bf16 v[98:101], v[164:167], v[196:199], 0
	v_mfma_f32_16x16x32_bf16 v[94:97], v[150:153], v[204:207], 0
	v_mfma_f32_16x16x32_bf16 v[90:93], v[164:167], v[204:207], 0
	v_mfma_f32_16x16x32_bf16 v[86:89], v[150:153], v[212:215], 0
	v_mfma_f32_16x16x32_bf16 v[82:85], v[164:167], v[212:215], 0
	v_mfma_f32_16x16x32_bf16 v[110:113], v[160:163], v[192:195], v[110:113]
	v_mfma_f32_16x16x32_bf16 v[106:109], v[168:171], v[192:195], v[106:109]
	v_mfma_f32_16x16x32_bf16 v[102:105], v[160:163], v[200:203], v[102:105]
	v_mfma_f32_16x16x32_bf16 v[98:101], v[168:171], v[200:203], v[98:101]
	v_mfma_f32_16x16x32_bf16 v[94:97], v[160:163], v[208:211], v[94:97]
	v_mfma_f32_16x16x32_bf16 v[90:93], v[168:171], v[208:211], v[90:93]
	v_mfma_f32_16x16x32_bf16 v[86:89], v[160:163], v[216:219], v[86:89]
	v_mfma_f32_16x16x32_bf16 v[82:85], v[168:171], v[216:219], v[82:85]
	v_mfma_f32_16x16x32_bf16 v[78:81], v[172:175], v[188:191], 0
	v_mfma_f32_16x16x32_bf16 v[74:77], v[180:183], v[188:191], 0
	v_mfma_f32_16x16x32_bf16 v[70:73], v[172:175], v[196:199], 0
	v_mfma_f32_16x16x32_bf16 v[66:69], v[180:183], v[196:199], 0
	v_mfma_f32_16x16x32_bf16 v[62:65], v[172:175], v[204:207], 0
	v_mfma_f32_16x16x32_bf16 v[58:61], v[180:183], v[204:207], 0
	v_mfma_f32_16x16x32_bf16 v[54:57], v[172:175], v[212:215], 0
	v_mfma_f32_16x16x32_bf16 v[50:53], v[180:183], v[212:215], 0
	v_mfma_f32_16x16x32_bf16 v[78:81], v[176:179], v[192:195], v[78:81]
	v_mfma_f32_16x16x32_bf16 v[74:77], v[184:187], v[192:195], v[74:77]
	v_mfma_f32_16x16x32_bf16 v[70:73], v[176:179], v[200:203], v[70:73]
	v_mfma_f32_16x16x32_bf16 v[66:69], v[184:187], v[200:203], v[66:69]
	v_mfma_f32_16x16x32_bf16 v[62:65], v[176:179], v[208:211], v[62:65]
	v_mfma_f32_16x16x32_bf16 v[58:61], v[184:187], v[208:211], v[58:61]
	v_mfma_f32_16x16x32_bf16 v[54:57], v[176:179], v[216:219], v[54:57]
	v_mfma_f32_16x16x32_bf16 v[50:53], v[184:187], v[216:219], v[50:53]
	s_barrier
	s_add_i32 s70, s54, s49
	v_lshl_add_u64 v[154:155], s[42:43], 0, v[132:133]
	s_mov_b32 m0, s70
	ds_read_b128 v[188:191], v159 offset:16384
	ds_read_b128 v[192:195], v238 offset:16384
	ds_read_b128 v[196:199], v159 offset:18432
	ds_read_b128 v[200:203], v238 offset:18432
	ds_read_b128 v[204:207], v159 offset:20480
	ds_read_b128 v[208:211], v238 offset:20480
	ds_read_b128 v[212:215], v159 offset:22528
	ds_read_b128 v[216:219], v238 offset:22528
	global_load_lds_dwordx4 v[154:155], off
	s_add_i32 m0, s70, 0x2000
	s_add_u32 s70, s42, 0x40000
	v_lshl_add_u64 v[220:221], s[42:43], 0, v[136:137]
	s_addc_u32 s71, s43, 0
	s_add_i32 s72, s55, s49
	global_load_lds_dwordx4 v[220:221], off
	v_lshl_add_u64 v[222:223], s[70:71], 0, v[132:133]
	s_mov_b32 m0, s72
	v_lshl_add_u64 v[224:225], s[44:45], 0, v[134:135]
	global_load_lds_dwordx4 v[222:223], off
	v_lshl_add_u64 v[222:223], s[70:71], 0, v[136:137]
	s_add_i32 m0, s72, 0x2000
	s_nop 0
	global_load_lds_dwordx4 v[222:223], off
	v_lshl_add_u64 v[222:223], s[44:45], 0, v[130:131]
	s_mov_b32 m0, s17
	s_nop 0
	global_load_lds_dwordx4 v[222:223], off
	s_mov_b32 m0, s19
	s_nop 0
	global_load_lds_dwordx4 v[224:225], off
	s_waitcnt vmcnt(8)
	s_waitcnt lgkmcnt(0)
	s_barrier
; #define PG8_STAGEA(bufoff, gbase) PG8_STAGE_(bufoff, gbase, voffA)
; #define PG8_LDA(dst, b, h) do { _Pragma("unroll") for (int m = 0; m < 4; ++m) _Pragma("unroll") for (int k = 0; k < 2; ++k) dst[m][k] = *(const LAS bf16x8*)(lds + PG8_SA(b, h) + aoff + m * 2048 + k * 1024); } while (0)
; #define PG8_LDB(dst, b, h) do { _Pragma("unroll") for (int n = 0; n < 2; ++n) _Pragma("unroll") for (int k = 0; k < 2; ++k) dst[n][k] = *(const LAS bf16x8*)(lds + PG8_SB(b, h) + boff + n * 2048 + k * 1024); } while (0)
; #define PG8_MMA(ai, bj, At, Bt_) do { __builtin_amdgcn_s_setprio(1); _Pragma("unroll") for (int m = 0; m < 4; ++m) _Pragma("unroll") for (int n = 0; n < 2; ++n) _Pragma("unroll") for (int k = 0; k < 2; ++k) \
;         acc[ai][bj][m][n] = __builtin_amdgcn_mfma_f32_16x16x32_bf16(Bt_[n][k], At[m][k], acc[ai][bj][m][n], 0, 0, 0); __builtin_amdgcn_s_setprio(0); } while (0)
; #define PG8_WAIT_V(n) asm volatile("s_waitcnt vmcnt(" #n ")" ::: "memory")
; #define PG8_WAIT_L(n) asm volatile("s_waitcnt lgkmcnt(" #n ")" ::: "memory")
; #define PG8_BAR __builtin_amdgcn_s_barrier()
; #define PG8_SCHED __builtin_amdgcn_sched_barrier(0)
; template <int EK, int SK = -1>
; __device__ __forceinline__ void gemm_phase(LAS unsigned char* lds, const bf16_t* A, const bf16_t* Bt, int nM, int N, int K, const EpiArgs& E) {
;     ...
;             PG8_WAIT_V(8); PG8_WAIT_L(0); PG8_BAR; PG8_MMA(1, 0, At, B0); PG8_MMA(1, 1, At, B1); PG8_BAR; PG8_SCHED;
;             PG8_LDB(B0, 1, 0); PG8_LDB(B1, 1, 1); PG8_SCHED; PG8_LDA(At, 1, 0); PG8_STAGEA(PG8_SA(0, 1), a2 + hstep);
;             PG8_WAIT_V(8); PG8_WAIT_L(0); PG8_BAR; PG8_MMA(0, 0, At, B0); PG8_MMA(0, 1, At, B1); PG8_BAR; PG8_SCHED;
	s_waitcnt lgkmcnt(0)
	v_mfma_f32_16x16x32_bf16 v[46:49], v[150:153], v[188:191], 0
	v_mfma_f32_16x16x32_bf16 v[42:45], v[164:167], v[188:191], 0
	v_mfma_f32_16x16x32_bf16 v[38:41], v[150:153], v[196:199], 0
	v_mfma_f32_16x16x32_bf16 v[34:37], v[164:167], v[196:199], 0
	v_mfma_f32_16x16x32_bf16 v[30:33], v[150:153], v[204:207], 0
	v_mfma_f32_16x16x32_bf16 v[26:29], v[164:167], v[204:207], 0
	v_mfma_f32_16x16x32_bf16 v[22:25], v[150:153], v[212:215], 0
	v_mfma_f32_16x16x32_bf16 v[18:21], v[164:167], v[212:215], 0
	v_mfma_f32_16x16x32_bf16 v[46:49], v[160:163], v[192:195], v[46:49]
	v_mfma_f32_16x16x32_bf16 v[42:45], v[168:171], v[192:195], v[42:45]
	v_mfma_f32_16x16x32_bf16 v[38:41], v[160:163], v[200:203], v[38:41]
	v_mfma_f32_16x16x32_bf16 v[34:37], v[168:171], v[200:203], v[34:37]
	v_mfma_f32_16x16x32_bf16 v[30:33], v[160:163], v[208:211], v[30:33]
	v_mfma_f32_16x16x32_bf16 v[26:29], v[168:171], v[208:211], v[26:29]
	v_mfma_f32_16x16x32_bf16 v[22:25], v[160:163], v[216:219], v[22:25]
	v_mfma_f32_16x16x32_bf16 v[18:21], v[168:171], v[216:219], v[18:21]
	v_mfma_f32_16x16x32_bf16 v[14:17], v[172:175], v[188:191], 0
	v_mfma_f32_16x16x32_bf16 v[10:13], v[180:183], v[188:191], 0
	v_mfma_f32_16x16x32_bf16 v[6:9], v[172:175], v[196:199], 0
	v_mfma_f32_16x16x32_bf16 v[2:5], v[180:183], v[196:199], 0
	v_mfma_f32_16x16x32_bf16 v[114:117], v[172:175], v[204:207], 0
	v_mfma_f32_16x16x32_bf16 v[118:121], v[180:183], v[204:207], 0
	v_mfma_f32_16x16x32_bf16 v[122:125], v[172:175], v[212:215], 0
	v_mfma_f32_16x16x32_bf16 v[126:129], v[180:183], v[212:215], 0
	v_mfma_f32_16x16x32_bf16 v[14:17], v[176:179], v[192:195], v[14:17]
	v_mfma_f32_16x16x32_bf16 v[10:13], v[184:187], v[192:195], v[10:13]
	v_mfma_f32_16x16x32_bf16 v[6:9], v[176:179], v[200:203], v[6:9]
	v_mfma_f32_16x16x32_bf16 v[2:5], v[184:187], v[200:203], v[2:5]
	v_mfma_f32_16x16x32_bf16 v[114:117], v[176:179], v[208:211], v[114:117]
	v_mfma_f32_16x16x32_bf16 v[118:121], v[184:187], v[208:211], v[118:121]
	v_mfma_f32_16x16x32_bf16 v[122:125], v[176:179], v[216:219], v[122:125]
	v_mfma_f32_16x16x32_bf16 v[126:129], v[184:187], v[216:219], v[126:129]
	s_barrier
	s_add_i32 s70, 0, 0x18000
	s_add_i32 s71, 0, 0x1c000
	v_add_u32_e32 v168, s70, v156
	v_add_u32_e32 v236, s70, v239
	v_add_u32_e32 v184, s71, v156
	v_add_u32_e32 v237, s71, v239
	ds_read_b128 v[150:153], v168
	ds_read_b128 v[160:163], v236
	ds_read_b128 v[164:167], v168 offset:2048
	ds_read_b128 v[168:171], v236 offset:2048
	ds_read_b128 v[172:175], v184
	ds_read_b128 v[176:179], v237
	ds_read_b128 v[180:183], v184 offset:2048
	ds_read_b128 v[184:187], v237 offset:2048
	s_add_u32 s44, s44, 0x40000
	s_addc_u32 s45, s45, 0
	s_mov_b32 m0, s50
	v_lshl_add_u64 v[226:227], s[44:45], 0, v[130:131]
	ds_read_b128 v[188:191], v159 offset:32768
	ds_read_b128 v[192:195], v238 offset:32768
	ds_read_b128 v[196:199], v159 offset:34816
	ds_read_b128 v[200:203], v238 offset:34816
	ds_read_b128 v[204:207], v159 offset:36864
	ds_read_b128 v[208:211], v238 offset:36864
	ds_read_b128 v[212:215], v159 offset:38912
	ds_read_b128 v[216:219], v238 offset:38912
	global_load_lds_dwordx4 v[226:227], off
	v_lshl_add_u64 v[226:227], s[44:45], 0, v[134:135]
	s_mov_b32 m0, s51
	s_nop 0
	global_load_lds_dwordx4 v[226:227], off
	s_waitcnt vmcnt(8)
	s_waitcnt lgkmcnt(0)
	s_barrier
	s_waitcnt lgkmcnt(0)
	v_mfma_f32_16x16x32_bf16 v[110:113], v[150:153], v[188:191], v[110:113]
	v_mfma_f32_16x16x32_bf16 v[106:109], v[164:167], v[188:191], v[106:109]
	v_mfma_f32_16x16x32_bf16 v[102:105], v[150:153], v[196:199], v[102:105]
	v_mfma_f32_16x16x32_bf16 v[98:101], v[164:167], v[196:199], v[98:101]
	v_mfma_f32_16x16x32_bf16 v[94:97], v[150:153], v[204:207], v[94:97]
	v_mfma_f32_16x16x32_bf16 v[90:93], v[164:167], v[204:207], v[90:93]
	v_mfma_f32_16x16x32_bf16 v[86:89], v[150:153], v[212:215], v[86:89]
	v_mfma_f32_16x16x32_bf16 v[82:85], v[164:167], v[212:215], v[82:85]
	v_mfma_f32_16x16x32_bf16 v[110:113], v[160:163], v[192:195], v[110:113]
	v_mfma_f32_16x16x32_bf16 v[106:109], v[168:171], v[192:195], v[106:109]
	v_mfma_f32_16x16x32_bf16 v[102:105], v[160:163], v[200:203], v[102:105]
	v_mfma_f32_16x16x32_bf16 v[98:101], v[168:171], v[200:203], v[98:101]
	v_mfma_f32_16x16x32_bf16 v[94:97], v[160:163], v[208:211], v[94:97]
	v_mfma_f32_16x16x32_bf16 v[90:93], v[168:171], v[208:211], v[90:93]
	v_mfma_f32_16x16x32_bf16 v[86:89], v[160:163], v[216:219], v[86:89]
	v_mfma_f32_16x16x32_bf16 v[82:85], v[168:171], v[216:219], v[82:85]
	v_mfma_f32_16x16x32_bf16 v[78:81], v[172:175], v[188:191], v[78:81]
	v_mfma_f32_16x16x32_bf16 v[74:77], v[180:183], v[188:191], v[74:77]
	v_mfma_f32_16x16x32_bf16 v[70:73], v[172:175], v[196:199], v[70:73]
	v_mfma_f32_16x16x32_bf16 v[66:69], v[180:183], v[196:199], v[66:69]
	v_mfma_f32_16x16x32_bf16 v[62:65], v[172:175], v[204:207], v[62:65]
	v_mfma_f32_16x16x32_bf16 v[58:61], v[180:183], v[204:207], v[58:61]
	v_mfma_f32_16x16x32_bf16 v[54:57], v[172:175], v[212:215], v[54:57]
	v_mfma_f32_16x16x32_bf16 v[50:53], v[180:183], v[212:215], v[50:53]
	v_mfma_f32_16x16x32_bf16 v[78:81], v[176:179], v[192:195], v[78:81]
	v_mfma_f32_16x16x32_bf16 v[74:77], v[184:187], v[192:195], v[74:77]
	v_mfma_f32_16x16x32_bf16 v[70:73], v[176:179], v[200:203], v[70:73]
	v_mfma_f32_16x16x32_bf16 v[66:69], v[184:187], v[200:203], v[66:69]
	v_mfma_f32_16x16x32_bf16 v[62:65], v[176:179], v[208:211], v[62:65]
	v_mfma_f32_16x16x32_bf16 v[58:61], v[184:187], v[208:211], v[58:61]
	v_mfma_f32_16x16x32_bf16 v[54:57], v[176:179], v[216:219], v[54:57]
	v_mfma_f32_16x16x32_bf16 v[50:53], v[184:187], v[216:219], v[50:53]
	s_barrier
; #define PG8_STAGEA(bufoff, gbase) PG8_STAGE_(bufoff, gbase, voffA)
; #define PG8_STAGEB(bufoff, gbase) PG8_STAGE_(bufoff, gbase, voffB)
; #define PG8_LDA(dst, b, h) do { _Pragma("unroll") for (int m = 0; m < 4; ++m) _Pragma("unroll") for (int k = 0; k < 2; ++k) dst[m][k] = *(const LAS bf16x8*)(lds + PG8_SA(b, h) + aoff + m * 2048 + k * 1024); } while (0)
; #define PG8_LDB(dst, b, h) do { _Pragma("unroll") for (int n = 0; n < 2; ++n) _Pragma("unroll") for (int k = 0; k < 2; ++k) dst[n][k] = *(const LAS bf16x8*)(lds + PG8_SB(b, h) + boff + n * 2048 + k * 1024); } while (0)
; #define PG8_MMA(ai, bj, At, Bt_) do { __builtin_amdgcn_s_setprio(1); _Pragma("unroll") for (int m = 0; m < 4; ++m) _Pragma("unroll") for (int n = 0; n < 2; ++n) _Pragma("unroll") for (int k = 0; k < 2; ++k) \
;         acc[ai][bj][m][n] = __builtin_amdgcn_mfma_f32_16x16x32_bf16(Bt_[n][k], At[m][k], acc[ai][bj][m][n], 0, 0, 0); __builtin_amdgcn_s_setprio(0); } while (0)
; #define PG8_WAIT_V(n) asm volatile("s_waitcnt vmcnt(" #n ")" ::: "memory")
; #define PG8_WAIT_L(n) asm volatile("s_waitcnt lgkmcnt(" #n ")" ::: "memory")
; #define PG8_BAR __builtin_amdgcn_s_barrier()
; #define PG8_SCHED __builtin_amdgcn_sched_barrier(0)
; template <int EK, int SK = -1>
; __device__ __forceinline__ void gemm_phase(LAS unsigned char* lds, const bf16_t* A, const bf16_t* Bt, int nM, int N, int K, const EpiArgs& E) {
;     ...
;             PG8_LDB(B0, 0, 0); PG8_LDB(B1, 0, 1); PG8_SCHED; PG8_LDA(At, 0, 0); PG8_STAGEA(PG8_SA(1, 1), a1 + hstep);
;             PG8_WAIT_V(8); PG8_WAIT_L(0); PG8_BAR; PG8_MMA(0, 0, At, B0); PG8_MMA(0, 1, At, B1); PG8_BAR; PG8_SCHED;
;     ...
;             PG8_LDA(At, 1, 1); PG8_STAGEB(PG8_SB(1, 0), b3); PG8_STAGEB(PG8_SB(1, 1), b3 + hstep); PG8_STAGEA(PG8_SA(1, 0), a3);
;             PG8_WAIT_V(8); PG8_WAIT_L(0); PG8_BAR; PG8_MMA(1, 0, At, B0); PG8_MMA(1, 1, At, B1); PG8_BAR; PG8_SCHED;
	s_add_i32 s44, s70, s49
	v_lshl_add_u64 v[154:155], v[154:155], 0, s[10:11]
	s_mov_b32 m0, s44
	ds_read_b128 v[188:191], v159 offset:49152
	ds_read_b128 v[192:195], v238 offset:49152
	ds_read_b128 v[196:199], v159 offset:51200
	ds_read_b128 v[200:203], v238 offset:51200
	ds_read_b128 v[204:207], v159 offset:53248
	ds_read_b128 v[208:211], v238 offset:53248
	ds_read_b128 v[212:215], v159 offset:55296
	ds_read_b128 v[216:219], v238 offset:55296
	global_load_lds_dwordx4 v[154:155], off
	s_add_i32 m0, s44, 0x2000
	s_add_u32 s42, s42, 0x40080
	v_lshl_add_u64 v[154:155], v[220:221], 0, s[10:11]
	s_addc_u32 s43, s43, 0
	s_add_i32 s44, s71, s49
	global_load_lds_dwordx4 v[154:155], off
	v_lshl_add_u64 v[154:155], s[42:43], 0, v[132:133]
	s_mov_b32 m0, s44
	s_nop 0
	global_load_lds_dwordx4 v[154:155], off
	v_lshl_add_u64 v[154:155], s[42:43], 0, v[136:137]
	s_add_i32 m0, s44, 0x2000
	s_nop 0
	global_load_lds_dwordx4 v[154:155], off
	v_lshl_add_u64 v[154:155], v[222:223], 0, s[10:11]
	s_mov_b32 m0, s52
	s_nop 0
	global_load_lds_dwordx4 v[154:155], off
	v_lshl_add_u64 v[154:155], v[224:225], 0, s[10:11]
	s_mov_b32 m0, s53
	s_nop 0
	global_load_lds_dwordx4 v[154:155], off
	s_waitcnt vmcnt(8)
	s_waitcnt lgkmcnt(0)
	s_barrier
	s_waitcnt lgkmcnt(0)
	v_mfma_f32_16x16x32_bf16 v[46:49], v[150:153], v[188:191], v[46:49]
	v_mfma_f32_16x16x32_bf16 v[42:45], v[164:167], v[188:191], v[42:45]
	v_mfma_f32_16x16x32_bf16 v[38:41], v[150:153], v[196:199], v[38:41]
	v_mfma_f32_16x16x32_bf16 v[34:37], v[164:167], v[196:199], v[34:37]
	v_mfma_f32_16x16x32_bf16 v[30:33], v[150:153], v[204:207], v[30:33]
	v_mfma_f32_16x16x32_bf16 v[26:29], v[164:167], v[204:207], v[26:29]
	v_mfma_f32_16x16x32_bf16 v[22:25], v[150:153], v[212:215], v[22:25]
	v_mfma_f32_16x16x32_bf16 v[18:21], v[164:167], v[212:215], v[18:21]
	v_mfma_f32_16x16x32_bf16 v[46:49], v[160:163], v[192:195], v[46:49]
	v_mfma_f32_16x16x32_bf16 v[42:45], v[168:171], v[192:195], v[42:45]
	v_mfma_f32_16x16x32_bf16 v[38:41], v[160:163], v[200:203], v[38:41]
	v_mfma_f32_16x16x32_bf16 v[34:37], v[168:171], v[200:203], v[34:37]
	v_mfma_f32_16x16x32_bf16 v[30:33], v[160:163], v[208:211], v[30:33]
	v_mfma_f32_16x16x32_bf16 v[26:29], v[168:171], v[208:211], v[26:29]
	v_mfma_f32_16x16x32_bf16 v[22:25], v[160:163], v[216:219], v[22:25]
	v_mfma_f32_16x16x32_bf16 v[18:21], v[168:171], v[216:219], v[18:21]
	v_mfma_f32_16x16x32_bf16 v[14:17], v[172:175], v[188:191], v[14:17]
	v_mfma_f32_16x16x32_bf16 v[10:13], v[180:183], v[188:191], v[10:13]
	v_mfma_f32_16x16x32_bf16 v[6:9], v[172:175], v[196:199], v[6:9]
	v_mfma_f32_16x16x32_bf16 v[2:5], v[180:183], v[196:199], v[2:5]
	v_mfma_f32_16x16x32_bf16 v[114:117], v[172:175], v[204:207], v[114:117]
	v_mfma_f32_16x16x32_bf16 v[118:121], v[180:183], v[204:207], v[118:121]
	v_mfma_f32_16x16x32_bf16 v[122:125], v[172:175], v[212:215], v[122:125]
	v_mfma_f32_16x16x32_bf16 v[126:129], v[180:183], v[212:215], v[126:129]
	v_mfma_f32_16x16x32_bf16 v[14:17], v[176:179], v[192:195], v[14:17]
	v_mfma_f32_16x16x32_bf16 v[10:13], v[184:187], v[192:195], v[10:13]
	v_mfma_f32_16x16x32_bf16 v[6:9], v[176:179], v[200:203], v[6:9]
	v_mfma_f32_16x16x32_bf16 v[2:5], v[184:187], v[200:203], v[2:5]
	v_mfma_f32_16x16x32_bf16 v[114:117], v[176:179], v[208:211], v[114:117]
	v_mfma_f32_16x16x32_bf16 v[118:121], v[184:187], v[208:211], v[118:121]
	v_mfma_f32_16x16x32_bf16 v[122:125], v[176:179], v[216:219], v[122:125]
	v_mfma_f32_16x16x32_bf16 v[126:129], v[184:187], v[216:219], v[126:129]
	s_barrier
	s_add_i32 s69, s69, 2
	s_add_u32 s40, s40, 0x100
	s_addc_u32 s41, s41, 0
	s_cmp_gt_u32 s69, 13
	s_cbranch_scc0 .LBB0_1245
	s_branch .Lmy_kexit_6
.LBB0_1245:
	v_add_u32_e32 v154, s54, v156
	v_add_u32_e32 v237, s54, v239
	ds_read_b128 v[150:153], v154
	ds_read_b128 v[160:163], v237
	ds_read_b128 v[164:167], v154 offset:2048
	ds_read_b128 v[168:171], v237 offset:2048
	v_add_u32_e32 v154, s55, v156
	v_add_u32_e32 v237, s55, v239
	s_add_u32 s42, s20, s40
	ds_read_b128 v[172:175], v154
	ds_read_b128 v[176:179], v237
	ds_read_b128 v[180:183], v154 offset:2048
	ds_read_b128 v[184:187], v237 offset:2048
	s_addc_u32 s43, s21, s41
	s_add_u32 s42, s42, 0x100
	s_addc_u32 s43, s43, 0
	s_add_u32 s70, s59, s40
	s_addc_u32 s71, s66, s41
	s_cmpk_eq_i32 s40, 0x700
	s_cselect_b32 s45, s27, s43
	s_cselect_b32 s44, s67, s42
	s_cselect_b32 s43, s23, s71
	s_cselect_b32 s42, s68, s70
	v_lshl_add_u64 v[154:155], v[146:147], 0, s[40:41]
	s_add_i32 m0, s17, 0xc000
	ds_read_b128 v[188:191], v159
	ds_read_b128 v[192:195], v238
	ds_read_b128 v[196:199], v159 offset:2048
	ds_read_b128 v[200:203], v238 offset:2048
	ds_read_b128 v[204:207], v159 offset:4096
	ds_read_b128 v[208:211], v238 offset:4096
	ds_read_b128 v[212:215], v159 offset:6144
	ds_read_b128 v[216:219], v238 offset:6144
	global_load_lds_dwordx4 v[154:155], off
	v_lshl_add_u64 v[154:155], v[148:149], 0, s[40:41]
	s_add_i32 m0, s17, 0xe000
	s_nop 0
	global_load_lds_dwordx4 v[154:155], off
	s_waitcnt vmcnt(8)
	s_waitcnt lgkmcnt(0)
	s_barrier
; #define PG8_STAGEA(bufoff, gbase) PG8_STAGE_(bufoff, gbase, voffA)
; #define PG8_STAGEB(bufoff, gbase) PG8_STAGE_(bufoff, gbase, voffB)
; #define PG8_LDA(dst, b, h) do { _Pragma("unroll") for (int m = 0; m < 4; ++m) _Pragma("unroll") for (int k = 0; k < 2; ++k) dst[m][k] = *(const LAS bf16x8*)(lds + PG8_SA(b, h) + aoff + m * 2048 + k * 1024); } while (0)
; #define PG8_MMA(ai, bj, At, Bt_) do { __builtin_amdgcn_s_setprio(1); _Pragma("unroll") for (int m = 0; m < 4; ++m) _Pragma("unroll") for (int n = 0; n < 2; ++n) _Pragma("unroll") for (int k = 0; k < 2; ++k) \
;         acc[ai][bj][m][n] = __builtin_amdgcn_mfma_f32_16x16x32_bf16(Bt_[n][k], At[m][k], acc[ai][bj][m][n], 0, 0, 0); __builtin_amdgcn_s_setprio(0); } while (0)
; #define PG8_WAIT_V(n) asm volatile("s_waitcnt vmcnt(" #n ")" ::: "memory")
; #define PG8_WAIT_L(n) asm volatile("s_waitcnt lgkmcnt(" #n ")" ::: "memory")
; #define PG8_BAR __builtin_amdgcn_s_barrier()
; #define PG8_SCHED __builtin_amdgcn_sched_barrier(0)
; template <int EK, int SK = -1>
; __device__ __forceinline__ void gemm_phase(LAS unsigned char* lds, const bf16_t* A, const bf16_t* Bt, int nM, int N, int K, const EpiArgs& E) {
;     ...
;             PG8_WAIT_V(8); PG8_WAIT_L(0); PG8_BAR; PG8_MMA(0, 0, At, B0); PG8_MMA(0, 1, At, B1); PG8_BAR; PG8_SCHED;
;             PG8_LDA(At, 0, 1); PG8_STAGEB(PG8_SB(0, 0), b2); PG8_STAGEB(PG8_SB(0, 1), b2 + hstep); PG8_STAGEA(PG8_SA(0, 0), a2);
;             PG8_WAIT_V(8); PG8_WAIT_L(0); PG8_BAR; PG8_MMA(1, 0, At, B0); PG8_MMA(1, 1, At, B1); PG8_BAR; PG8_SCHED;
	s_waitcnt lgkmcnt(0)
	v_mfma_f32_16x16x32_bf16 v[110:113], v[150:153], v[188:191], v[110:113]
	v_mfma_f32_16x16x32_bf16 v[106:109], v[164:167], v[188:191], v[106:109]
	v_mfma_f32_16x16x32_bf16 v[102:105], v[150:153], v[196:199], v[102:105]
	v_mfma_f32_16x16x32_bf16 v[98:101], v[164:167], v[196:199], v[98:101]
	v_mfma_f32_16x16x32_bf16 v[94:97], v[150:153], v[204:207], v[94:97]
	v_mfma_f32_16x16x32_bf16 v[90:93], v[164:167], v[204:207], v[90:93]
	v_mfma_f32_16x16x32_bf16 v[86:89], v[150:153], v[212:215], v[86:89]
	v_mfma_f32_16x16x32_bf16 v[82:85], v[164:167], v[212:215], v[82:85]
	v_mfma_f32_16x16x32_bf16 v[110:113], v[160:163], v[192:195], v[110:113]
	v_mfma_f32_16x16x32_bf16 v[106:109], v[168:171], v[192:195], v[106:109]
	v_mfma_f32_16x16x32_bf16 v[102:105], v[160:163], v[200:203], v[102:105]
	v_mfma_f32_16x16x32_bf16 v[98:101], v[168:171], v[200:203], v[98:101]
	v_mfma_f32_16x16x32_bf16 v[94:97], v[160:163], v[208:211], v[94:97]
	v_mfma_f32_16x16x32_bf16 v[90:93], v[168:171], v[208:211], v[90:93]
	v_mfma_f32_16x16x32_bf16 v[86:89], v[160:163], v[216:219], v[86:89]
	v_mfma_f32_16x16x32_bf16 v[82:85], v[168:171], v[216:219], v[82:85]
	v_mfma_f32_16x16x32_bf16 v[78:81], v[172:175], v[188:191], v[78:81]
	v_mfma_f32_16x16x32_bf16 v[74:77], v[180:183], v[188:191], v[74:77]
	v_mfma_f32_16x16x32_bf16 v[70:73], v[172:175], v[196:199], v[70:73]
	v_mfma_f32_16x16x32_bf16 v[66:69], v[180:183], v[196:199], v[66:69]
	v_mfma_f32_16x16x32_bf16 v[62:65], v[172:175], v[204:207], v[62:65]
	v_mfma_f32_16x16x32_bf16 v[58:61], v[180:183], v[204:207], v[58:61]
	v_mfma_f32_16x16x32_bf16 v[54:57], v[172:175], v[212:215], v[54:57]
	v_mfma_f32_16x16x32_bf16 v[50:53], v[180:183], v[212:215], v[50:53]
	v_mfma_f32_16x16x32_bf16 v[78:81], v[176:179], v[192:195], v[78:81]
	v_mfma_f32_16x16x32_bf16 v[74:77], v[184:187], v[192:195], v[74:77]
	v_mfma_f32_16x16x32_bf16 v[70:73], v[176:179], v[200:203], v[70:73]
	v_mfma_f32_16x16x32_bf16 v[66:69], v[184:187], v[200:203], v[66:69]
	v_mfma_f32_16x16x32_bf16 v[62:65], v[176:179], v[208:211], v[62:65]
	v_mfma_f32_16x16x32_bf16 v[58:61], v[184:187], v[208:211], v[58:61]
	v_mfma_f32_16x16x32_bf16 v[54:57], v[176:179], v[216:219], v[54:57]
	v_mfma_f32_16x16x32_bf16 v[50:53], v[184:187], v[216:219], v[50:53]
	s_barrier
	s_add_i32 s70, s54, s49
	v_lshl_add_u64 v[154:155], s[42:43], 0, v[132:133]
	s_mov_b32 m0, s70
	ds_read_b128 v[188:191], v159 offset:16384
	ds_read_b128 v[192:195], v238 offset:16384
	ds_read_b128 v[196:199], v159 offset:18432
	ds_read_b128 v[200:203], v238 offset:18432
	ds_read_b128 v[204:207], v159 offset:20480
	ds_read_b128 v[208:211], v238 offset:20480
	ds_read_b128 v[212:215], v159 offset:22528
	ds_read_b128 v[216:219], v238 offset:22528
	global_load_lds_dwordx4 v[154:155], off
	s_add_i32 m0, s70, 0x2000
	s_add_u32 s70, s42, 0x40000
	v_lshl_add_u64 v[220:221], s[42:43], 0, v[136:137]
	s_addc_u32 s71, s43, 0
	s_add_i32 s72, s55, s49
	global_load_lds_dwordx4 v[220:221], off
	v_lshl_add_u64 v[222:223], s[70:71], 0, v[132:133]
	s_mov_b32 m0, s72
	v_lshl_add_u64 v[224:225], s[44:45], 0, v[134:135]
	global_load_lds_dwordx4 v[222:223], off
	v_lshl_add_u64 v[222:223], s[70:71], 0, v[136:137]
	s_add_i32 m0, s72, 0x2000
	s_nop 0
	global_load_lds_dwordx4 v[222:223], off
	v_lshl_add_u64 v[222:223], s[44:45], 0, v[130:131]
	s_mov_b32 m0, s17
	s_nop 0
	global_load_lds_dwordx4 v[222:223], off
	s_mov_b32 m0, s19
	s_nop 0
	global_load_lds_dwordx4 v[224:225], off
	s_waitcnt vmcnt(8)
	s_waitcnt lgkmcnt(0)
	s_barrier
	s_waitcnt lgkmcnt(0)
	v_mfma_f32_16x16x32_bf16 v[46:49], v[150:153], v[188:191], v[46:49]
	v_mfma_f32_16x16x32_bf16 v[42:45], v[164:167], v[188:191], v[42:45]
	v_mfma_f32_16x16x32_bf16 v[38:41], v[150:153], v[196:199], v[38:41]
	v_mfma_f32_16x16x32_bf16 v[34:37], v[164:167], v[196:199], v[34:37]
	v_mfma_f32_16x16x32_bf16 v[30:33], v[150:153], v[204:207], v[30:33]
	v_mfma_f32_16x16x32_bf16 v[26:29], v[164:167], v[204:207], v[26:29]
	v_mfma_f32_16x16x32_bf16 v[22:25], v[150:153], v[212:215], v[22:25]
	v_mfma_f32_16x16x32_bf16 v[18:21], v[164:167], v[212:215], v[18:21]
	v_mfma_f32_16x16x32_bf16 v[46:49], v[160:163], v[192:195], v[46:49]
	v_mfma_f32_16x16x32_bf16 v[42:45], v[168:171], v[192:195], v[42:45]
	v_mfma_f32_16x16x32_bf16 v[38:41], v[160:163], v[200:203], v[38:41]
	v_mfma_f32_16x16x32_bf16 v[34:37], v[168:171], v[200:203], v[34:37]
	v_mfma_f32_16x16x32_bf16 v[30:33], v[160:163], v[208:211], v[30:33]
	v_mfma_f32_16x16x32_bf16 v[26:29], v[168:171], v[208:211], v[26:29]
	v_mfma_f32_16x16x32_bf16 v[22:25], v[160:163], v[216:219], v[22:25]
	v_mfma_f32_16x16x32_bf16 v[18:21], v[168:171], v[216:219], v[18:21]
	v_mfma_f32_16x16x32_bf16 v[14:17], v[172:175], v[188:191], v[14:17]
	v_mfma_f32_16x16x32_bf16 v[10:13], v[180:183], v[188:191], v[10:13]
	v_mfma_f32_16x16x32_bf16 v[6:9], v[172:175], v[196:199], v[6:9]
	v_mfma_f32_16x16x32_bf16 v[2:5], v[180:183], v[196:199], v[2:5]
	v_mfma_f32_16x16x32_bf16 v[114:117], v[172:175], v[204:207], v[114:117]
	v_mfma_f32_16x16x32_bf16 v[118:121], v[180:183], v[204:207], v[118:121]
	v_mfma_f32_16x16x32_bf16 v[122:125], v[172:175], v[212:215], v[122:125]
	v_mfma_f32_16x16x32_bf16 v[126:129], v[180:183], v[212:215], v[126:129]
	v_mfma_f32_16x16x32_bf16 v[14:17], v[176:179], v[192:195], v[14:17]
	v_mfma_f32_16x16x32_bf16 v[10:13], v[184:187], v[192:195], v[10:13]
	v_mfma_f32_16x16x32_bf16 v[6:9], v[176:179], v[200:203], v[6:9]
	v_mfma_f32_16x16x32_bf16 v[2:5], v[184:187], v[200:203], v[2:5]
	v_mfma_f32_16x16x32_bf16 v[114:117], v[176:179], v[208:211], v[114:117]
	v_mfma_f32_16x16x32_bf16 v[118:121], v[184:187], v[208:211], v[118:121]
	v_mfma_f32_16x16x32_bf16 v[122:125], v[176:179], v[216:219], v[122:125]
	v_mfma_f32_16x16x32_bf16 v[126:129], v[184:187], v[216:219], v[126:129]
	s_barrier
; #define PG8_STAGEA(bufoff, gbase) PG8_STAGE_(bufoff, gbase, voffA)
; #define PG8_STAGEB(bufoff, gbase) PG8_STAGE_(bufoff, gbase, voffB)
; #define PG8_LDA(dst, b, h) do { _Pragma("unroll") for (int m = 0; m < 4; ++m) _Pragma("unroll") for (int k = 0; k < 2; ++k) dst[m][k] = *(const LAS bf16x8*)(lds + PG8_SA(b, h) + aoff + m * 2048 + k * 1024); } while (0)
; #define PG8_LDB(dst, b, h) do { _Pragma("unroll") for (int n = 0; n < 2; ++n) _Pragma("unroll") for (int k = 0; k < 2; ++k) dst[n][k] = *(const LAS bf16x8*)(lds + PG8_SB(b, h) + boff + n * 2048 + k * 1024); } while (0)
; #define PG8_MMA(ai, bj, At, Bt_) do { __builtin_amdgcn_s_setprio(1); _Pragma("unroll") for (int m = 0; m < 4; ++m) _Pragma("unroll") for (int n = 0; n < 2; ++n) _Pragma("unroll") for (int k = 0; k < 2; ++k) \
;         acc[ai][bj][m][n] = __builtin_amdgcn_mfma_f32_16x16x32_bf16(Bt_[n][k], At[m][k], acc[ai][bj][m][n], 0, 0, 0); __builtin_amdgcn_s_setprio(0); } while (0)
; #define PG8_WAIT_V(n) asm volatile("s_waitcnt vmcnt(" #n ")" ::: "memory")
; #define PG8_WAIT_L(n) asm volatile("s_waitcnt lgkmcnt(" #n ")" ::: "memory")
; #define PG8_BAR __builtin_amdgcn_s_barrier()
; #define PG8_SCHED __builtin_amdgcn_sched_barrier(0)
; template <int EK, int SK = -1>
; __device__ __forceinline__ void gemm_phase(LAS unsigned char* lds, const bf16_t* A, const bf16_t* Bt, int nM, int N, int K, const EpiArgs& E) {
;     ...
;             PG8_LDB(B0, 1, 0); PG8_LDB(B1, 1, 1); PG8_SCHED; PG8_LDA(At, 1, 0); PG8_STAGEA(PG8_SA(0, 1), a2 + hstep);
;             PG8_WAIT_V(8); PG8_WAIT_L(0); PG8_BAR; PG8_MMA(0, 0, At, B0); PG8_MMA(0, 1, At, B1); PG8_BAR; PG8_SCHED;
;             PG8_LDA(At, 1, 1); PG8_STAGEB(PG8_SB(1, 0), b3); PG8_STAGEB(PG8_SB(1, 1), b3 + hstep); PG8_STAGEA(PG8_SA(1, 0), a3);
;             PG8_WAIT_V(8); PG8_WAIT_L(0); PG8_BAR; PG8_MMA(1, 0, At, B0); PG8_MMA(1, 1, At, B1); PG8_BAR; PG8_SCHED;
	s_add_i32 s70, 0, 0x18000
	s_add_i32 s71, 0, 0x1c000
	v_add_u32_e32 v168, s70, v156
	v_add_u32_e32 v236, s70, v239
	v_add_u32_e32 v184, s71, v156
	v_add_u32_e32 v237, s71, v239
	ds_read_b128 v[150:153], v168
	ds_read_b128 v[160:163], v236
	ds_read_b128 v[164:167], v168 offset:2048
	ds_read_b128 v[168:171], v236 offset:2048
	ds_read_b128 v[172:175], v184
	ds_read_b128 v[176:179], v237
	ds_read_b128 v[180:183], v184 offset:2048
	ds_read_b128 v[184:187], v237 offset:2048
	s_add_u32 s44, s44, 0x40000
	s_addc_u32 s45, s45, 0
	s_mov_b32 m0, s50
	v_lshl_add_u64 v[226:227], s[44:45], 0, v[130:131]
	ds_read_b128 v[188:191], v159 offset:32768
	ds_read_b128 v[192:195], v238 offset:32768
	ds_read_b128 v[196:199], v159 offset:34816
	ds_read_b128 v[200:203], v238 offset:34816
	ds_read_b128 v[204:207], v159 offset:36864
	ds_read_b128 v[208:211], v238 offset:36864
	ds_read_b128 v[212:215], v159 offset:38912
	ds_read_b128 v[216:219], v238 offset:38912
	global_load_lds_dwordx4 v[226:227], off
	v_lshl_add_u64 v[226:227], s[44:45], 0, v[134:135]
	s_mov_b32 m0, s51
	s_nop 0
	global_load_lds_dwordx4 v[226:227], off
	s_waitcnt vmcnt(8)
	s_waitcnt lgkmcnt(0)
	s_barrier
	s_waitcnt lgkmcnt(0)
	v_mfma_f32_16x16x32_bf16 v[110:113], v[150:153], v[188:191], v[110:113]
	v_mfma_f32_16x16x32_bf16 v[106:109], v[164:167], v[188:191], v[106:109]
	v_mfma_f32_16x16x32_bf16 v[102:105], v[150:153], v[196:199], v[102:105]
	v_mfma_f32_16x16x32_bf16 v[98:101], v[164:167], v[196:199], v[98:101]
	v_mfma_f32_16x16x32_bf16 v[94:97], v[150:153], v[204:207], v[94:97]
	v_mfma_f32_16x16x32_bf16 v[90:93], v[164:167], v[204:207], v[90:93]
	v_mfma_f32_16x16x32_bf16 v[86:89], v[150:153], v[212:215], v[86:89]
	v_mfma_f32_16x16x32_bf16 v[82:85], v[164:167], v[212:215], v[82:85]
	v_mfma_f32_16x16x32_bf16 v[110:113], v[160:163], v[192:195], v[110:113]
	v_mfma_f32_16x16x32_bf16 v[106:109], v[168:171], v[192:195], v[106:109]
	v_mfma_f32_16x16x32_bf16 v[102:105], v[160:163], v[200:203], v[102:105]
	v_mfma_f32_16x16x32_bf16 v[98:101], v[168:171], v[200:203], v[98:101]
	v_mfma_f32_16x16x32_bf16 v[94:97], v[160:163], v[208:211], v[94:97]
	v_mfma_f32_16x16x32_bf16 v[90:93], v[168:171], v[208:211], v[90:93]
	v_mfma_f32_16x16x32_bf16 v[86:89], v[160:163], v[216:219], v[86:89]
	v_mfma_f32_16x16x32_bf16 v[82:85], v[168:171], v[216:219], v[82:85]
	v_mfma_f32_16x16x32_bf16 v[78:81], v[172:175], v[188:191], v[78:81]
	v_mfma_f32_16x16x32_bf16 v[74:77], v[180:183], v[188:191], v[74:77]
	v_mfma_f32_16x16x32_bf16 v[70:73], v[172:175], v[196:199], v[70:73]
	v_mfma_f32_16x16x32_bf16 v[66:69], v[180:183], v[196:199], v[66:69]
	v_mfma_f32_16x16x32_bf16 v[62:65], v[172:175], v[204:207], v[62:65]
	v_mfma_f32_16x16x32_bf16 v[58:61], v[180:183], v[204:207], v[58:61]
	v_mfma_f32_16x16x32_bf16 v[54:57], v[172:175], v[212:215], v[54:57]
	v_mfma_f32_16x16x32_bf16 v[50:53], v[180:183], v[212:215], v[50:53]
	v_mfma_f32_16x16x32_bf16 v[78:81], v[176:179], v[192:195], v[78:81]
	v_mfma_f32_16x16x32_bf16 v[74:77], v[184:187], v[192:195], v[74:77]
	v_mfma_f32_16x16x32_bf16 v[70:73], v[176:179], v[200:203], v[70:73]
	v_mfma_f32_16x16x32_bf16 v[66:69], v[184:187], v[200:203], v[66:69]
	v_mfma_f32_16x16x32_bf16 v[62:65], v[176:179], v[208:211], v[62:65]
	v_mfma_f32_16x16x32_bf16 v[58:61], v[184:187], v[208:211], v[58:61]
	v_mfma_f32_16x16x32_bf16 v[54:57], v[176:179], v[216:219], v[54:57]
	v_mfma_f32_16x16x32_bf16 v[50:53], v[184:187], v[216:219], v[50:53]
	s_barrier
	s_add_i32 s44, s70, s49
	v_lshl_add_u64 v[154:155], v[154:155], 0, s[10:11]
	s_mov_b32 m0, s44
	ds_read_b128 v[188:191], v159 offset:49152
	ds_read_b128 v[192:195], v238 offset:49152
	ds_read_b128 v[196:199], v159 offset:51200
	ds_read_b128 v[200:203], v238 offset:51200
	ds_read_b128 v[204:207], v159 offset:53248
	ds_read_b128 v[208:211], v238 offset:53248
	ds_read_b128 v[212:215], v159 offset:55296
	ds_read_b128 v[216:219], v238 offset:55296
	global_load_lds_dwordx4 v[154:155], off
	s_add_i32 m0, s44, 0x2000
	s_add_u32 s42, s42, 0x40080
	v_lshl_add_u64 v[154:155], v[220:221], 0, s[10:11]
	s_addc_u32 s43, s43, 0
	s_add_i32 s44, s71, s49
	global_load_lds_dwordx4 v[154:155], off
	v_lshl_add_u64 v[154:155], s[42:43], 0, v[132:133]
	s_mov_b32 m0, s44
	s_nop 0
	global_load_lds_dwordx4 v[154:155], off
	v_lshl_add_u64 v[154:155], s[42:43], 0, v[136:137]
	s_add_i32 m0, s44, 0x2000
	s_nop 0
	global_load_lds_dwordx4 v[154:155], off
	v_lshl_add_u64 v[154:155], v[222:223], 0, s[10:11]
	s_mov_b32 m0, s52
	s_nop 0
	global_load_lds_dwordx4 v[154:155], off
	v_lshl_add_u64 v[154:155], v[224:225], 0, s[10:11]
	s_mov_b32 m0, s53
	s_nop 0
	global_load_lds_dwordx4 v[154:155], off
	s_waitcnt vmcnt(8)
	s_waitcnt lgkmcnt(0)
	s_barrier
	s_waitcnt lgkmcnt(0)
	v_mfma_f32_16x16x32_bf16 v[46:49], v[150:153], v[188:191], v[46:49]
	v_mfma_f32_16x16x32_bf16 v[42:45], v[164:167], v[188:191], v[42:45]
	v_mfma_f32_16x16x32_bf16 v[38:41], v[150:153], v[196:199], v[38:41]
	v_mfma_f32_16x16x32_bf16 v[34:37], v[164:167], v[196:199], v[34:37]
	v_mfma_f32_16x16x32_bf16 v[30:33], v[150:153], v[204:207], v[30:33]
	v_mfma_f32_16x16x32_bf16 v[26:29], v[164:167], v[204:207], v[26:29]
	v_mfma_f32_16x16x32_bf16 v[22:25], v[150:153], v[212:215], v[22:25]
	v_mfma_f32_16x16x32_bf16 v[18:21], v[164:167], v[212:215], v[18:21]
	v_mfma_f32_16x16x32_bf16 v[46:49], v[160:163], v[192:195], v[46:49]
	v_mfma_f32_16x16x32_bf16 v[42:45], v[168:171], v[192:195], v[42:45]
	v_mfma_f32_16x16x32_bf16 v[38:41], v[160:163], v[200:203], v[38:41]
	v_mfma_f32_16x16x32_bf16 v[34:37], v[168:171], v[200:203], v[34:37]
	v_mfma_f32_16x16x32_bf16 v[30:33], v[160:163], v[208:211], v[30:33]
	v_mfma_f32_16x16x32_bf16 v[26:29], v[168:171], v[208:211], v[26:29]
	v_mfma_f32_16x16x32_bf16 v[22:25], v[160:163], v[216:219], v[22:25]
	v_mfma_f32_16x16x32_bf16 v[18:21], v[168:171], v[216:219], v[18:21]
	v_mfma_f32_16x16x32_bf16 v[14:17], v[172:175], v[188:191], v[14:17]
	v_mfma_f32_16x16x32_bf16 v[10:13], v[180:183], v[188:191], v[10:13]
	v_mfma_f32_16x16x32_bf16 v[6:9], v[172:175], v[196:199], v[6:9]
	v_mfma_f32_16x16x32_bf16 v[2:5], v[180:183], v[196:199], v[2:5]
	v_mfma_f32_16x16x32_bf16 v[114:117], v[172:175], v[204:207], v[114:117]
	v_mfma_f32_16x16x32_bf16 v[118:121], v[180:183], v[204:207], v[118:121]
	v_mfma_f32_16x16x32_bf16 v[122:125], v[172:175], v[212:215], v[122:125]
	v_mfma_f32_16x16x32_bf16 v[126:129], v[180:183], v[212:215], v[126:129]
	v_mfma_f32_16x16x32_bf16 v[14:17], v[176:179], v[192:195], v[14:17]
	v_mfma_f32_16x16x32_bf16 v[10:13], v[184:187], v[192:195], v[10:13]
	v_mfma_f32_16x16x32_bf16 v[6:9], v[176:179], v[200:203], v[6:9]
	v_mfma_f32_16x16x32_bf16 v[2:5], v[184:187], v[200:203], v[2:5]
	v_mfma_f32_16x16x32_bf16 v[114:117], v[176:179], v[208:211], v[114:117]
	v_mfma_f32_16x16x32_bf16 v[118:121], v[184:187], v[208:211], v[118:121]
	v_mfma_f32_16x16x32_bf16 v[122:125], v[176:179], v[216:219], v[122:125]
	v_mfma_f32_16x16x32_bf16 v[126:129], v[184:187], v[216:219], v[126:129]
	s_barrier
	s_add_i32 s69, s69, 2
	s_add_u32 s40, s40, 0x100
	s_addc_u32 s41, s41, 0
	s_cmp_gt_u32 s69, 13
	s_cbranch_scc0 .LBB0_1245
